# nt stores for prologue bf16 weights; hand-scheduled rmsnorm (k=6) row loop; residual epilogue with 16 loads in flight
# speedup vs baseline: 1.0161x; 1.0161x over previous
.LBB2_101:
	s_or_b64 exec, exec, s[0:1]
	s_waitcnt vmcnt(7)
	v_pk_mul_f32 v[4:5], v[72:73], v[4:5] op_sel_hi:[0,1]
	v_pk_mul_f32 v[2:3], v[72:73], v[2:3] op_sel_hi:[0,1]
	ds_write2_b32 v73, v2, v3 offset1:1
	ds_write2_b32 v73, v4, v5 offset0:2 offset1:3
	s_waitcnt vmcnt(6)
	v_pk_mul_f32 v[4:5], v[70:71], v[6:7] op_sel_hi:[0,1]
	v_add_u32_e32 v6, 0x420, v73
	v_pk_mul_f32 v[2:3], v[70:71], v[8:9] op_sel_hi:[0,1]
	ds_write2_b32 v6, v4, v5 offset1:1
	v_add_u32_e32 v4, 0x428, v73
	ds_write2_b32 v4, v2, v3 offset1:1
	s_waitcnt vmcnt(5)
	v_pk_mul_f32 v[4:5], v[76:77], v[10:11] op_sel_hi:[0,1]
	v_add_u32_e32 v6, 0x840, v73
	v_pk_mul_f32 v[2:3], v[76:77], v[12:13] op_sel_hi:[0,1]
	ds_write2_b32 v6, v4, v5 offset1:1
	v_add_u32_e32 v4, 0x848, v73
	ds_write2_b32 v4, v2, v3 offset1:1
	s_waitcnt vmcnt(4)
	v_pk_mul_f32 v[4:5], v[74:75], v[14:15] op_sel_hi:[0,1]
	v_add_u32_e32 v6, 0xc60, v73
	v_pk_mul_f32 v[2:3], v[74:75], v[16:17] op_sel_hi:[0,1]
	ds_write2_b32 v6, v4, v5 offset1:1
	v_add_u32_e32 v4, 0xc68, v73
	ds_write2_b32 v4, v2, v3 offset1:1
	s_waitcnt vmcnt(3)
	v_pk_mul_f32 v[4:5], v[80:81], v[18:19] op_sel_hi:[0,1]
	v_add_u32_e32 v6, 0x1080, v73
	v_pk_mul_f32 v[2:3], v[80:81], v[20:21] op_sel_hi:[0,1]
	ds_write2_b32 v6, v4, v5 offset1:1
	v_add_u32_e32 v4, 0x1088, v73
	ds_write2_b32 v4, v2, v3 offset1:1
	s_waitcnt vmcnt(2)
	v_pk_mul_f32 v[4:5], v[78:79], v[22:23] op_sel_hi:[0,1]
	v_add_u32_e32 v6, 0x14a0, v73
	v_pk_mul_f32 v[2:3], v[78:79], v[24:25] op_sel_hi:[0,1]
	ds_write2_b32 v6, v4, v5 offset1:1
	v_add_u32_e32 v4, 0x14a8, v73
	ds_write2_b32 v4, v2, v3 offset1:1
	s_waitcnt vmcnt(1)
	v_pk_mul_f32 v[4:5], v[102:103], v[26:27] op_sel_hi:[0,1]
	v_add_u32_e32 v6, 0x18c0, v73
	v_pk_mul_f32 v[2:3], v[102:103], v[28:29] op_sel_hi:[0,1]
	ds_write2_b32 v6, v4, v5 offset1:1
	v_add_u32_e32 v4, 0x18c8, v73
	ds_write2_b32 v4, v2, v3 offset1:1
	s_waitcnt vmcnt(0)
	v_pk_mul_f32 v[4:5], v[94:95], v[30:31] op_sel_hi:[0,1]
	v_add_u32_e32 v6, 0x1ce0, v73
	v_pk_mul_f32 v[2:3], v[94:95], v[32:33] op_sel_hi:[0,1]
	ds_write2_b32 v6, v4, v5 offset1:1
	v_add_u32_e32 v4, 0x1ce8, v73
	ds_write2_b32 v4, v2, v3 offset1:1
	s_waitcnt lgkmcnt(0)
	ds_read2_b32 v[2:3], v71 offset1:33
	s_waitcnt lgkmcnt(0)
	v_cvt_pk_bf16_f32 v2, v2, v3
	ds_read2_b32 v[4:5], v71 offset0:66 offset1:99
	v_mov_b32_e32 v105, v85
	s_waitcnt lgkmcnt(0)
	v_cvt_pk_bf16_f32 v3, v4, v5
	ds_read2_b32 v[4:5], v71 offset0:132 offset1:165
	v_lshl_add_u64 v[8:9], v[68:69], 0, v[104:105]
	v_mad_i64_i32 v[10:11], s[0:1], v67, v66, 0
	s_waitcnt lgkmcnt(0)
	v_cvt_pk_bf16_f32 v4, v4, v5
	ds_read2_b32 v[6:7], v71 offset0:198 offset1:231
	s_waitcnt lgkmcnt(0)
	v_cvt_pk_bf16_f32 v5, v6, v7
	v_lshl_add_u64 v[10:11], v[10:11], 1, v[8:9]
	ds_read2_b32 v[6:7], v71 offset0:8 offset1:41
	global_store_dwordx4 v[10:11], v[2:5], off nt
	v_mad_i64_i32 v[10:11], s[0:1], v67, v86, 0
	s_waitcnt lgkmcnt(0)
	v_cvt_pk_bf16_f32 v2, v6, v7
	ds_read2_b32 v[4:5], v71 offset0:74 offset1:107
	s_waitcnt lgkmcnt(0)
	v_cvt_pk_bf16_f32 v3, v4, v5
	ds_read2_b32 v[4:5], v71 offset0:140 offset1:173
	s_waitcnt lgkmcnt(0)
	v_cvt_pk_bf16_f32 v4, v4, v5
	ds_read2_b32 v[6:7], v71 offset0:206 offset1:239
	s_waitcnt lgkmcnt(0)
	v_cvt_pk_bf16_f32 v5, v6, v7
	v_lshl_add_u64 v[10:11], v[10:11], 1, v[8:9]
	ds_read2_b32 v[6:7], v71 offset0:16 offset1:49
	global_store_dwordx4 v[10:11], v[2:5], off nt
	v_mad_i64_i32 v[10:11], s[0:1], v67, v88, 0
	s_waitcnt lgkmcnt(0)
	v_cvt_pk_bf16_f32 v2, v6, v7
	ds_read2_b32 v[4:5], v71 offset0:82 offset1:115
	s_waitcnt lgkmcnt(0)
	v_cvt_pk_bf16_f32 v3, v4, v5
	ds_read2_b32 v[4:5], v71 offset0:148 offset1:181
	s_waitcnt lgkmcnt(0)
	v_cvt_pk_bf16_f32 v4, v4, v5
	ds_read2_b32 v[6:7], v71 offset0:214 offset1:247
	s_waitcnt lgkmcnt(0)
	v_cvt_pk_bf16_f32 v5, v6, v7
	v_lshl_add_u64 v[10:11], v[10:11], 1, v[8:9]
	ds_read2_b32 v[6:7], v71 offset0:24 offset1:57
	global_store_dwordx4 v[10:11], v[2:5], off nt
	v_mov_b64_e32 v[68:69], v[106:107]
	v_mov_b32_e32 v72, v83
	s_waitcnt lgkmcnt(0)
	v_cvt_pk_bf16_f32 v2, v6, v7
	ds_read2_b32 v[4:5], v71 offset0:90 offset1:123
	s_waitcnt lgkmcnt(0)
	v_cvt_pk_bf16_f32 v3, v4, v5
	ds_read2_b32 v[4:5], v71 offset0:156 offset1:189
	s_waitcnt lgkmcnt(0)
	v_cvt_pk_bf16_f32 v4, v4, v5
	ds_read2_b32 v[6:7], v71 offset0:222 offset1:255
	s_waitcnt lgkmcnt(0)
	v_cvt_pk_bf16_f32 v5, v6, v7
	v_mad_i64_i32 v[6:7], s[0:1], v67, v90, 0
	v_lshl_add_u64 v[6:7], v[6:7], 1, v[8:9]
	global_store_dwordx4 v[6:7], v[2:5], off nt
	s_waitcnt lgkmcnt(0)
	v_mov_b32_e32 v67, v99
	v_mov_b32_e32 v70, v87
	v_mov_b32_e32 v76, v81
	v_mov_b32_e32 v74, v89
	v_mov_b32_e32 v80, v93
	v_mov_b32_e32 v78, v95
	v_mov_b32_e32 v102, v91
	v_mov_b32_e32 v94, v97
	v_mov_b32_e32 v2, v34
	v_mov_b32_e32 v3, v35
	v_mov_b32_e32 v4, v36
	v_mov_b32_e32 v5, v37
	v_mov_b32_e32 v6, v38
	v_mov_b32_e32 v7, v39
	v_mov_b32_e32 v8, v40
	v_mov_b32_e32 v9, v41
	v_mov_b32_e32 v10, v42
	v_mov_b32_e32 v11, v43
	v_mov_b32_e32 v12, v44
	v_mov_b32_e32 v13, v45
	v_mov_b32_e32 v14, v50
	v_mov_b32_e32 v15, v51
	v_mov_b32_e32 v16, v52
	v_mov_b32_e32 v17, v53
	v_mov_b32_e32 v18, v46
	v_mov_b32_e32 v19, v47
	v_mov_b32_e32 v20, v48
	v_mov_b32_e32 v21, v49
	v_mov_b32_e32 v22, v54
	v_mov_b32_e32 v23, v55
	v_mov_b32_e32 v24, v56
	v_mov_b32_e32 v25, v57
	v_mov_b32_e32 v26, v58
	v_mov_b32_e32 v27, v59
	v_mov_b32_e32 v28, v60
	v_mov_b32_e32 v29, v61
	v_mov_b32_e32 v30, v62
	v_mov_b32_e32 v31, v63
	v_mov_b32_e32 v32, v64
	v_mov_b32_e32 v33, v65
	s_andn2_b64 exec, exec, s[34:35]
	s_cbranch_execz .LBB2_165

.LBB2_213:
	v_mov_b32_e32 v0, v146
	v_readlane_b32 s2, v252, 44
	s_waitcnt lgkmcnt(0)
	v_ashrrev_i32_e32 v2, 6, v0
	v_add_u32_e32 v34, s2, v2
	s_movk_i32 s2, 0x2000
	v_cmp_gt_i32_e32 vcc, s2, v34
	s_and_saveexec_b64 s[2:3], vcc
	v_readlane_b32 s8, v254, 41
	v_readlane_b32 s9, v254, 42
	s_cbranch_execz .LBB2_216
	v_and_b32_e32 v4, 63, v0
	v_and_b32_e32 v0, 64, v189
	v_add_u32_e32 v0, 64, v0
	v_xor_b32_e32 v2, 1, v189
	v_cmp_lt_i32_e32 vcc, v2, v0
	v_readlane_b32 s4, v254, 46
	v_readlane_b32 s5, v254, 47
	v_cndmask_b32_e32 v2, v189, v2, vcc
	v_lshlrev_b32_e32 v54, 2, v2
	v_xor_b32_e32 v2, 2, v189
	v_cmp_lt_i32_e32 vcc, v2, v0
	v_readlane_b32 s36, v252, 23
	s_lshl_b64 s[4:5], s[4:5], 13
	v_cndmask_b32_e32 v2, v189, v2, vcc
	v_lshlrev_b32_e32 v55, 2, v2
	v_xor_b32_e32 v2, 4, v189
	v_cmp_lt_i32_e32 vcc, v2, v0
	v_readlane_b32 s42, v252, 29
	v_readlane_b32 s43, v252, 30
	v_cndmask_b32_e32 v2, v189, v2, vcc
	v_lshlrev_b32_e32 v56, 2, v2
	v_xor_b32_e32 v2, 8, v189
	v_cmp_lt_i32_e32 vcc, v2, v0
	s_add_u32 s4, s42, s4
	s_addc_u32 s5, s43, s5
	v_cndmask_b32_e32 v2, v189, v2, vcc
	v_lshlrev_b32_e32 v57, 2, v2
	v_xor_b32_e32 v2, 16, v189
	v_cmp_lt_i32_e32 vcc, v2, v0
	v_mov_b32_e32 v3, v1
	v_ashrrev_i32_e32 v35, 31, v34
	v_cndmask_b32_e32 v2, v189, v2, vcc
	v_lshlrev_b32_e32 v58, 2, v2
	v_xor_b32_e32 v2, 32, v189
	v_cmp_lt_i32_e32 vcc, v2, v0
	v_readlane_b32 s37, v252, 24
	v_readlane_b32 s38, v252, 25
	v_cndmask_b32_e32 v0, v189, v2, vcc
	v_lshlrev_b32_e32 v59, 2, v0
	v_lshlrev_b32_e32 v0, 4, v4
	v_or_b32_e32 v2, 0x1000, v0
	v_lshl_add_u64 v[38:39], s[4:5], 0, v[2:3]
	v_or_b32_e32 v2, 0x1400, v0
	v_lshl_add_u64 v[40:41], s[4:5], 0, v[2:3]
	v_or_b32_e32 v2, 0x1800, v0
	v_lshl_add_u64 v[42:43], s[4:5], 0, v[2:3]
	v_or_b32_e32 v2, 0x1c00, v0
	v_lshl_add_u64 v[36:37], s[4:5], 0, v[0:1]
	v_lshl_add_u64 v[44:45], s[4:5], 0, v[2:3]
	v_lshlrev_b64 v[2:3], 12, v[34:35]
	v_readlane_b32 s4, v254, 48
	v_lshl_or_b32 v2, v4, 3, v2
	v_readlane_b32 s5, v254, 49
	v_readlane_b32 s39, v252, 26
	v_readlane_b32 s40, v252, 27
	v_lshl_add_u64 v[2:3], s[4:5], 0, v[2:3]
	s_mov_b64 s[4:5], 0x1800000
	v_lshl_add_u64 v[46:47], v[2:3], 0, s[4:5]
	v_lshlrev_b64 v[2:3], 13, v[34:35]
	v_readlane_b32 s4, v254, 27
	v_or_b32_e32 v2, v2, v0
	v_readlane_b32 s5, v254, 28
	v_readlane_b32 s41, v252, 28
	v_readlane_b32 s44, v252, 31
	v_lshl_add_u64 v[48:49], s[4:5], 0, v[2:3]
	s_mov_b64 s[4:5], 0
	v_readlane_b32 s45, v252, 32
	v_readlane_b32 s46, v252, 33
	v_readlane_b32 s47, v252, 34
	v_readlane_b32 s48, v252, 35
	v_readlane_b32 s49, v252, 36
	v_readlane_b32 s50, v252, 37
	v_readlane_b32 s51, v252, 38
	global_load_dwordx4 v[64:67], v[36:37], off
	global_load_dwordx4 v[68:71], v[36:37], off offset:1024
	global_load_dwordx4 v[72:75], v[36:37], off offset:2048
	global_load_dwordx4 v[76:79], v[36:37], off offset:3072
	global_load_dwordx4 v[80:83], v[38:39], off
	global_load_dwordx4 v[84:87], v[40:41], off
	global_load_dwordx4 v[88:91], v[42:43], off
	global_load_dwordx4 v[92:95], v[44:45], off
.Lnorm6_loop:
	global_load_dwordx4 v[96:99], v[48:49], off offset:-4096
	global_load_dwordx4 v[100:103], v[48:49], off offset:-3072
	global_load_dwordx4 v[104:107], v[48:49], off offset:-2048
	global_load_dwordx4 v[108:111], v[48:49], off offset:-1024
	global_load_dwordx4 v[112:115], v[48:49], off
	global_load_dwordx4 v[116:119], v[48:49], off offset:1024
	global_load_dwordx4 v[120:123], v[48:49], off offset:2048
	global_load_dwordx4 v[124:127], v[48:49], off offset:3072
	v_add_u32_e32 v34, s22, v34
	s_movk_i32 s6, 0x1fff
	v_lshl_add_u64 v[48:49], v[48:49], 0, s[20:21]
	s_waitcnt vmcnt(0)
	v_mul_f32_e32 v2, v96, v96
	v_mul_f32_e32 v3, v98, v98
	v_fmac_f32_e32 v2, v97, v97
	v_fmac_f32_e32 v3, v99, v99
	v_add_f32_e32 v0, v2, v3
	v_mul_f32_e32 v2, v100, v100
	v_mul_f32_e32 v3, v102, v102
	v_fmac_f32_e32 v2, v101, v101
	v_fmac_f32_e32 v3, v103, v103
	v_add_f32_e32 v2, v2, v3
	v_add_f32_e32 v0, v0, v2
	v_mul_f32_e32 v2, v104, v104
	v_mul_f32_e32 v3, v106, v106
	v_fmac_f32_e32 v2, v105, v105
	v_fmac_f32_e32 v3, v107, v107
	v_add_f32_e32 v2, v2, v3
	v_add_f32_e32 v0, v0, v2
	v_mul_f32_e32 v2, v108, v108
	v_mul_f32_e32 v3, v110, v110
	v_fmac_f32_e32 v2, v109, v109
	v_fmac_f32_e32 v3, v111, v111
	v_add_f32_e32 v2, v2, v3
	v_add_f32_e32 v0, v0, v2
	v_mul_f32_e32 v2, v112, v112
	v_mul_f32_e32 v3, v114, v114
	v_fmac_f32_e32 v2, v113, v113
	v_fmac_f32_e32 v3, v115, v115
	v_add_f32_e32 v2, v2, v3
	v_add_f32_e32 v0, v0, v2
	v_mul_f32_e32 v2, v116, v116
	v_mul_f32_e32 v3, v118, v118
	v_fmac_f32_e32 v2, v117, v117
	v_fmac_f32_e32 v3, v119, v119
	v_add_f32_e32 v2, v2, v3
	v_add_f32_e32 v0, v0, v2
	v_mul_f32_e32 v2, v120, v120
	v_mul_f32_e32 v3, v122, v122
	v_fmac_f32_e32 v2, v121, v121
	v_fmac_f32_e32 v3, v123, v123
	v_add_f32_e32 v2, v2, v3
	v_add_f32_e32 v0, v0, v2
	v_mul_f32_e32 v2, v124, v124
	v_mul_f32_e32 v3, v126, v126
	v_fmac_f32_e32 v2, v125, v125
	v_fmac_f32_e32 v3, v127, v127
	v_add_f32_e32 v2, v2, v3
	v_add_f32_e32 v0, v0, v2
	ds_bpermute_b32 v35, v54, v0
	s_waitcnt lgkmcnt(0)
	v_add_f32_e32 v0, v0, v35
	ds_bpermute_b32 v35, v55, v0
	s_waitcnt lgkmcnt(0)
	v_add_f32_e32 v0, v0, v35
	ds_bpermute_b32 v35, v56, v0
	s_waitcnt lgkmcnt(0)
	v_add_f32_e32 v0, v0, v35
	ds_bpermute_b32 v35, v57, v0
	s_waitcnt lgkmcnt(0)
	v_add_f32_e32 v0, v0, v35
	ds_bpermute_b32 v35, v58, v0
	s_waitcnt lgkmcnt(0)
	v_add_f32_e32 v0, v0, v35
	ds_bpermute_b32 v35, v59, v0
	s_waitcnt lgkmcnt(0)
	v_add_f32_e32 v0, v0, v35
	v_fmamk_f32 v0, v0, 0x3a000000, v147
	v_cmp_gt_f32_e32 vcc, s29, v0
	v_mul_f32_e32 v35, 0x4b800000, v0
	s_nop 0
	v_cndmask_b32_e32 v0, v0, v35, vcc
	v_rsq_f32_e32 v0, v0
	s_nop 0
	v_mul_f32_e32 v35, 0x45800000, v0
	v_cndmask_b32_e32 v0, v0, v35, vcc
	v_mul_f32_e32 v2, v96, v0
	v_mul_f32_e32 v3, v97, v0
	v_mul_f32_e32 v4, v98, v0
	v_mul_f32_e32 v5, v99, v0
	v_mul_f32_e32 v2, v2, v64
	v_mul_f32_e32 v3, v3, v65
	v_mul_f32_e32 v4, v4, v66
	v_mul_f32_e32 v5, v5, v67
	v_cvt_pk_bf16_f32 v128, v2, v3
	v_cvt_pk_bf16_f32 v129, v4, v5
	global_store_dwordx2 v[46:47], v[128:129], off
	v_mul_f32_e32 v2, v100, v0
	v_mul_f32_e32 v3, v101, v0
	v_mul_f32_e32 v4, v102, v0
	v_mul_f32_e32 v5, v103, v0
	v_mul_f32_e32 v2, v2, v68
	v_mul_f32_e32 v3, v3, v69
	v_mul_f32_e32 v4, v4, v70
	v_mul_f32_e32 v5, v5, v71
	v_cvt_pk_bf16_f32 v130, v2, v3
	v_cvt_pk_bf16_f32 v131, v4, v5
	global_store_dwordx2 v[46:47], v[130:131], off offset:512
	v_mul_f32_e32 v2, v104, v0
	v_mul_f32_e32 v3, v105, v0
	v_mul_f32_e32 v4, v106, v0
	v_mul_f32_e32 v5, v107, v0
	v_mul_f32_e32 v2, v2, v72
	v_mul_f32_e32 v3, v3, v73
	v_mul_f32_e32 v4, v4, v74
	v_mul_f32_e32 v5, v5, v75
	v_cvt_pk_bf16_f32 v132, v2, v3
	v_cvt_pk_bf16_f32 v133, v4, v5
	global_store_dwordx2 v[46:47], v[132:133], off offset:1024
	v_mul_f32_e32 v2, v108, v0
	v_mul_f32_e32 v3, v109, v0
	v_mul_f32_e32 v4, v110, v0
	v_mul_f32_e32 v5, v111, v0
	v_mul_f32_e32 v2, v2, v76
	v_mul_f32_e32 v3, v3, v77
	v_mul_f32_e32 v4, v4, v78
	v_mul_f32_e32 v5, v5, v79
	v_cvt_pk_bf16_f32 v134, v2, v3
	v_cvt_pk_bf16_f32 v135, v4, v5
	global_store_dwordx2 v[46:47], v[134:135], off offset:1536
	v_mul_f32_e32 v2, v112, v0
	v_mul_f32_e32 v3, v113, v0
	v_mul_f32_e32 v4, v114, v0
	v_mul_f32_e32 v5, v115, v0
	v_mul_f32_e32 v2, v2, v80
	v_mul_f32_e32 v3, v3, v81
	v_mul_f32_e32 v4, v4, v82
	v_mul_f32_e32 v5, v5, v83
	v_cvt_pk_bf16_f32 v136, v2, v3
	v_cvt_pk_bf16_f32 v137, v4, v5
	global_store_dwordx2 v[46:47], v[136:137], off offset:2048
	v_mul_f32_e32 v2, v116, v0
	v_mul_f32_e32 v3, v117, v0
	v_mul_f32_e32 v4, v118, v0
	v_mul_f32_e32 v5, v119, v0
	v_mul_f32_e32 v2, v2, v84
	v_mul_f32_e32 v3, v3, v85
	v_mul_f32_e32 v4, v4, v86
	v_mul_f32_e32 v5, v5, v87
	v_cvt_pk_bf16_f32 v138, v2, v3
	v_cvt_pk_bf16_f32 v139, v4, v5
	global_store_dwordx2 v[46:47], v[138:139], off offset:2560
	v_mul_f32_e32 v2, v120, v0
	v_mul_f32_e32 v3, v121, v0
	v_mul_f32_e32 v4, v122, v0
	v_mul_f32_e32 v5, v123, v0
	v_mul_f32_e32 v2, v2, v88
	v_mul_f32_e32 v3, v3, v89
	v_mul_f32_e32 v4, v4, v90
	v_mul_f32_e32 v5, v5, v91
	v_cvt_pk_bf16_f32 v140, v2, v3
	v_cvt_pk_bf16_f32 v141, v4, v5
	global_store_dwordx2 v[46:47], v[140:141], off offset:3072
	v_mul_f32_e32 v2, v124, v0
	v_mul_f32_e32 v3, v125, v0
	v_mul_f32_e32 v4, v126, v0
	v_mul_f32_e32 v5, v127, v0
	v_mul_f32_e32 v2, v2, v92
	v_mul_f32_e32 v3, v3, v93
	v_mul_f32_e32 v4, v4, v94
	v_mul_f32_e32 v5, v5, v95
	v_cvt_pk_bf16_f32 v142, v2, v3
	v_cvt_pk_bf16_f32 v143, v4, v5
	global_store_dwordx2 v[46:47], v[142:143], off offset:3584
	v_cmp_lt_i32_e32 vcc, s6, v34
	s_or_b64 s[4:5], vcc, s[4:5]
	v_lshl_add_u64 v[46:47], v[46:47], 0, s[8:9]
	s_andn2_b64 exec, exec, s[4:5]
	s_cbranch_execnz .Lnorm6_loop

.LBB2_235:
	v_lshl_add_u32 v144, s14, 8, v160
	v_lshl_or_b32 v142, s11, 8, v162
	v_ashrrev_i32_e32 v145, 31, v144
	v_ashrrev_i32_e32 v143, 31, v142
	v_lshlrev_b64 v[140:141], 11, v[144:145]
	v_lshl_add_u64 v[140:141], v[140:141], 0, v[142:143]
	v_readlane_b32 s8, v254, 44
	v_lshlrev_b64 v[140:141], 2, v[140:141]
	v_readlane_b32 s9, v254, 45
	v_readlane_b32 s56, v252, 23
	v_readlane_b32 s68, v252, 35
	v_lshl_add_u64 v[168:169], s[8:9], 0, v[140:141]
	v_readlane_b32 s69, v252, 36
	v_readlane_b32 s70, v252, 37
	v_readlane_b32 s71, v252, 38
	s_mov_b64 s[20:21], s[68:69]
	s_mov_b64 s[22:23], s[70:71]
	s_andn2_b64 vcc, exec, s[36:37]
	v_readlane_b32 s57, v252, 24
	v_readlane_b32 s58, v252, 25
	v_readlane_b32 s59, v252, 26
	v_readlane_b32 s60, v252, 27
	v_readlane_b32 s61, v252, 28
	v_readlane_b32 s62, v252, 29
	v_readlane_b32 s63, v252, 30
	v_readlane_b32 s64, v252, 31
	v_readlane_b32 s65, v252, 32
	v_readlane_b32 s66, v252, 33
	v_readlane_b32 s67, v252, 34
	v_lshl_add_u64 v[140:141], s[22:23], 0, v[140:141]
	s_mov_b64 s[100:101], 0x20000
	global_load_dwordx4 v[192:195], v[168:169], off
	global_load_dwordx4 v[196:199], v[168:169], off offset:16
	global_load_dwordx4 v[200:203], v[168:169], off offset:512
	global_load_dwordx4 v[204:207], v[168:169], off offset:528
	v_lshl_add_u64 v[168:169], v[168:169], 0, s[100:101]
	global_load_dwordx4 v[208:211], v[168:169], off
	global_load_dwordx4 v[212:215], v[168:169], off offset:16
	global_load_dwordx4 v[216:219], v[168:169], off offset:512
	global_load_dwordx4 v[220:223], v[168:169], off offset:528
	v_lshl_add_u64 v[168:169], v[168:169], 0, s[100:101]
	global_load_dwordx4 v[224:227], v[168:169], off
	global_load_dwordx4 v[228:231], v[168:169], off offset:16
	global_load_dwordx4 v[232:235], v[168:169], off offset:512
	global_load_dwordx4 v[236:239], v[168:169], off offset:528
	v_lshl_add_u64 v[168:169], v[168:169], 0, s[100:101]
	global_load_dwordx4 v[170:173], v[168:169], off
	global_load_dwordx4 v[174:177], v[168:169], off offset:16
	global_load_dwordx4 v[178:181], v[168:169], off offset:512
	global_load_dwordx4 v[182:185], v[168:169], off offset:528
	v_lshl_add_u64 v[168:169], s[100:101], 2, v[168:169]
	v_lshl_add_u64 v[168:169], v[168:169], 0, s[100:101]
	s_waitcnt vmcnt(12)
	v_pk_add_f32 v[126:127], v[126:127], v[192:193]
	v_pk_add_f32 v[128:129], v[128:129], v[194:195]
	v_pk_add_f32 v[122:123], v[122:123], v[196:197]
	v_pk_add_f32 v[124:125], v[124:125], v[198:199]
	v_pk_add_f32 v[118:119], v[118:119], v[200:201]
	v_pk_add_f32 v[120:121], v[120:121], v[202:203]
	v_pk_add_f32 v[114:115], v[114:115], v[204:205]
	v_pk_add_f32 v[116:117], v[116:117], v[206:207]
	global_store_dwordx4 v[140:141], v[126:129], off
	global_store_dwordx4 v[140:141], v[122:125], off offset:16
	global_store_dwordx4 v[140:141], v[118:121], off offset:512
	global_store_dwordx4 v[140:141], v[114:117], off offset:528
	v_lshl_add_u64 v[140:141], v[140:141], 0, s[100:101]
	global_load_dwordx4 v[192:195], v[168:169], off
	global_load_dwordx4 v[196:199], v[168:169], off offset:16
	global_load_dwordx4 v[200:203], v[168:169], off offset:512
	global_load_dwordx4 v[204:207], v[168:169], off offset:528
	v_lshl_add_u64 v[168:169], v[168:169], 0, s[100:101]
	s_waitcnt vmcnt(16)
	v_pk_add_f32 v[110:111], v[110:111], v[208:209]
	v_pk_add_f32 v[112:113], v[112:113], v[210:211]
	v_pk_add_f32 v[106:107], v[106:107], v[212:213]
	v_pk_add_f32 v[108:109], v[108:109], v[214:215]
	v_pk_add_f32 v[102:103], v[102:103], v[216:217]
	v_pk_add_f32 v[104:105], v[104:105], v[218:219]
	v_pk_add_f32 v[98:99], v[98:99], v[220:221]
	v_pk_add_f32 v[100:101], v[100:101], v[222:223]
	global_store_dwordx4 v[140:141], v[110:113], off
	global_store_dwordx4 v[140:141], v[106:109], off offset:16
	global_store_dwordx4 v[140:141], v[102:105], off offset:512
	global_store_dwordx4 v[140:141], v[98:101], off offset:528
	v_lshl_add_u64 v[140:141], v[140:141], 0, s[100:101]
	global_load_dwordx4 v[208:211], v[168:169], off
	global_load_dwordx4 v[212:215], v[168:169], off offset:16
	global_load_dwordx4 v[216:219], v[168:169], off offset:512
	global_load_dwordx4 v[220:223], v[168:169], off offset:528
	v_lshl_add_u64 v[168:169], v[168:169], 0, s[100:101]
	s_waitcnt vmcnt(20)
	v_pk_add_f32 v[94:95], v[94:95], v[224:225]
	v_pk_add_f32 v[96:97], v[96:97], v[226:227]
	v_pk_add_f32 v[90:91], v[90:91], v[228:229]
	v_pk_add_f32 v[92:93], v[92:93], v[230:231]
	v_pk_add_f32 v[86:87], v[86:87], v[232:233]
	v_pk_add_f32 v[88:89], v[88:89], v[234:235]
	v_pk_add_f32 v[82:83], v[82:83], v[236:237]
	v_pk_add_f32 v[84:85], v[84:85], v[238:239]
	global_store_dwordx4 v[140:141], v[94:97], off
	global_store_dwordx4 v[140:141], v[90:93], off offset:16
	global_store_dwordx4 v[140:141], v[86:89], off offset:512
	global_store_dwordx4 v[140:141], v[82:85], off offset:528
	v_lshl_add_u64 v[140:141], v[140:141], 0, s[100:101]
	global_load_dwordx4 v[224:227], v[168:169], off
	global_load_dwordx4 v[228:231], v[168:169], off offset:16
	global_load_dwordx4 v[232:235], v[168:169], off offset:512
	global_load_dwordx4 v[236:239], v[168:169], off offset:528
	v_lshl_add_u64 v[168:169], v[168:169], 0, s[100:101]
	s_waitcnt vmcnt(24)
	v_pk_add_f32 v[78:79], v[78:79], v[170:171]
	v_pk_add_f32 v[80:81], v[80:81], v[172:173]
	v_pk_add_f32 v[74:75], v[74:75], v[174:175]
	v_pk_add_f32 v[76:77], v[76:77], v[176:177]
	v_pk_add_f32 v[70:71], v[70:71], v[178:179]
	v_pk_add_f32 v[72:73], v[72:73], v[180:181]
	v_pk_add_f32 v[66:67], v[66:67], v[182:183]
	v_pk_add_f32 v[68:69], v[68:69], v[184:185]
	global_store_dwordx4 v[140:141], v[78:81], off
	global_store_dwordx4 v[140:141], v[74:77], off offset:16
	global_store_dwordx4 v[140:141], v[70:73], off offset:512
	global_store_dwordx4 v[140:141], v[66:69], off offset:528
	v_lshl_add_u64 v[140:141], s[100:101], 2, v[140:141]
	v_lshl_add_u64 v[140:141], v[140:141], 0, s[100:101]
	global_load_dwordx4 v[170:173], v[168:169], off
	global_load_dwordx4 v[174:177], v[168:169], off offset:16
	global_load_dwordx4 v[178:181], v[168:169], off offset:512
	global_load_dwordx4 v[182:185], v[168:169], off offset:528
	s_waitcnt vmcnt(24)
	v_pk_add_f32 v[62:63], v[62:63], v[192:193]
	v_pk_add_f32 v[64:65], v[64:65], v[194:195]
	v_pk_add_f32 v[58:59], v[58:59], v[196:197]
	v_pk_add_f32 v[60:61], v[60:61], v[198:199]
	v_pk_add_f32 v[54:55], v[54:55], v[200:201]
	v_pk_add_f32 v[56:57], v[56:57], v[202:203]
	v_pk_add_f32 v[50:51], v[50:51], v[204:205]
	v_pk_add_f32 v[52:53], v[52:53], v[206:207]
	global_store_dwordx4 v[140:141], v[62:65], off
	global_store_dwordx4 v[140:141], v[58:61], off offset:16
	global_store_dwordx4 v[140:141], v[54:57], off offset:512
	global_store_dwordx4 v[140:141], v[50:53], off offset:528
	v_lshl_add_u64 v[140:141], v[140:141], 0, s[100:101]
	s_waitcnt vmcnt(20)
	v_pk_add_f32 v[46:47], v[46:47], v[208:209]
	v_pk_add_f32 v[48:49], v[48:49], v[210:211]
	v_pk_add_f32 v[42:43], v[42:43], v[212:213]
	v_pk_add_f32 v[44:45], v[44:45], v[214:215]
	v_pk_add_f32 v[38:39], v[38:39], v[216:217]
	v_pk_add_f32 v[40:41], v[40:41], v[218:219]
	v_pk_add_f32 v[34:35], v[34:35], v[220:221]
	v_pk_add_f32 v[36:37], v[36:37], v[222:223]
	global_store_dwordx4 v[140:141], v[46:49], off
	global_store_dwordx4 v[140:141], v[42:45], off offset:16
	global_store_dwordx4 v[140:141], v[38:41], off offset:512
	global_store_dwordx4 v[140:141], v[34:37], off offset:528
	v_lshl_add_u64 v[140:141], v[140:141], 0, s[100:101]
	s_waitcnt vmcnt(16)
	v_pk_add_f32 v[30:31], v[30:31], v[224:225]
	v_pk_add_f32 v[32:33], v[32:33], v[226:227]
	v_pk_add_f32 v[26:27], v[26:27], v[228:229]
	v_pk_add_f32 v[28:29], v[28:29], v[230:231]
	v_pk_add_f32 v[22:23], v[22:23], v[232:233]
	v_pk_add_f32 v[24:25], v[24:25], v[234:235]
	v_pk_add_f32 v[18:19], v[18:19], v[236:237]
	v_pk_add_f32 v[20:21], v[20:21], v[238:239]
	global_store_dwordx4 v[140:141], v[30:33], off
	global_store_dwordx4 v[140:141], v[26:29], off offset:16
	global_store_dwordx4 v[140:141], v[22:25], off offset:512
	global_store_dwordx4 v[140:141], v[18:21], off offset:528
	v_lshl_add_u64 v[140:141], v[140:141], 0, s[100:101]
	s_waitcnt vmcnt(12)
	v_pk_add_f32 v[14:15], v[14:15], v[170:171]
	v_pk_add_f32 v[16:17], v[16:17], v[172:173]
	v_pk_add_f32 v[10:11], v[10:11], v[174:175]
	v_pk_add_f32 v[12:13], v[12:13], v[176:177]
	v_pk_add_f32 v[6:7], v[6:7], v[178:179]
	v_pk_add_f32 v[8:9], v[8:9], v[180:181]
	v_pk_add_f32 v[2:3], v[2:3], v[182:183]
	v_pk_add_f32 v[4:5], v[4:5], v[184:185]
	global_store_dwordx4 v[140:141], v[14:17], off
	global_store_dwordx4 v[140:141], v[10:13], off offset:16
	global_store_dwordx4 v[140:141], v[6:9], off offset:512
	global_store_dwordx4 v[140:141], v[2:5], off offset:528
	s_mov_b64 s[2:3], -1
	s_cbranch_vccnz .LBB2_224
	s_andn2_b64 vcc, exec, s[4:5]
	s_cbranch_vccnz .LBB2_223
	s_barrier
	s_branch .LBB2_223

.LBB2_332:
	s_and_b32 s11, s57, 7
	s_ashr_i32 s6, s58, 3
	s_lshl_b32 s0, s11, 8
	s_and_b32 s1, s58, 7
	s_ashr_i32 s7, s6, 31
	s_mul_i32 s3, s6, 0xc0000
	s_mul_hi_i32 s2, s6, 0xc0000
	s_add_u32 s3, s8, s3
	s_addc_u32 s4, s9, s2
	s_mul_i32 s5, s1, 0x180
	s_add_u32 s2, s3, s5
	s_addc_u32 s3, s4, 0
	s_add_u32 s14, s16, s5
	s_addc_u32 s15, s30, 0
	s_lshl_b32 s5, s1, 7
	s_lshl_b32 s1, s1, 8
	v_mov_b32_e32 v58, v146
	s_add_u32 s18, s31, s1
	s_addc_u32 s19, s38, 0
	v_readfirstlane_b32 s1, v58
	s_ashr_i32 s59, s1, 6
	v_and_b32_e32 v191, 31, v58
	s_lshl_b32 s4, s59, 5
	v_bfe_u32 v192, v58, 5, 1
	v_or_b32_e32 v0, s4, v191
	s_waitcnt lgkmcnt(0)
	v_mov_b64_e32 v[2:3], s[2:3]
	s_movk_i32 s20, 0xc00
	v_mad_i64_i32 v[2:3], s[2:3], v0, s20, v[2:3]
	v_lshlrev_b32_e32 v162, 4, v192
	v_mov_b32_e32 v163, v1
	v_lshl_add_u64 v[2:3], v[2:3], 0, v[162:163]
	s_ashr_i32 s3, s1, 4
	s_waitcnt vmcnt(0)
	v_lshrrev_b32_e32 v8, 1, v58
	flat_load_dwordx4 v[142:145], v[2:3]
	flat_load_dwordx4 v[138:141], v[2:3] offset:32
	flat_load_dwordx4 v[134:137], v[2:3] offset:64
	flat_load_dwordx4 v[130:133], v[2:3] offset:96
	flat_load_dwordx4 v[126:129], v[2:3] offset:128
	flat_load_dwordx4 v[122:125], v[2:3] offset:160
	flat_load_dwordx4 v[118:121], v[2:3] offset:192
	flat_load_dwordx4 v[114:117], v[2:3] offset:224
	flat_load_dwordx4 v[110:113], v[2:3] offset:256
	flat_load_dwordx4 v[106:109], v[2:3] offset:288
	flat_load_dwordx4 v[102:105], v[2:3] offset:320
	flat_load_dwordx4 v[98:101], v[2:3] offset:352
	v_and_b32_e32 v2, 8, v8
	s_lshr_b32 s2, s3, 1
	v_bfe_u32 v61, v58, 2, 2
	s_and_b32 s2, s2, 4
	v_and_or_b32 v62, s3, -16, v2
	v_bfe_u32 v0, v58, 3, 3
	v_or3_b32 v2, v62, v61, s2
	v_lshlrev_b32_e32 v161, 3, v58
	v_lshl_or_b32 v59, s59, 3, v0
	s_lshl_b32 s3, s59, 1
	v_and_b32_e32 v63, 24, v161
	v_ashrrev_i32_e32 v3, 31, v2
	v_lshrrev_b32_e32 v60, 1, v59
	v_and_or_b32 v4, s3, 2, v192
	v_lshlrev_b64 v[2:3], 11, v[2:3]
	v_lshlrev_b32_e32 v5, 1, v63
	v_xor_b32_e32 v0, v60, v58
	v_lshl_add_u64 v[2:3], s[18:19], 0, v[2:3]
	v_lshl_or_b32 v4, v4, 6, v5
	v_mov_b32_e32 v5, v1
	v_lshl_add_u64 v[2:3], v[2:3], 0, v[4:5]
	v_mov_b64_e32 v[4:5], s[14:15]
	v_lshlrev_b32_e32 v0, 4, v0
	s_lshl_b32 s3, s59, 10
	v_mad_i64_i32 v[4:5], s[14:15], v59, s20, v[4:5]
	v_and_b32_e32 v6, 0x70, v0
	v_mov_b32_e32 v7, v1
	s_add_i32 s61, s3, 0
	v_lshl_add_u64 v[4:5], v[4:5], 0, v[6:7]
	s_mov_b32 m0, s61
	v_lshl_add_u64 v[6:7], v[4:5], 0, s[34:35]
	global_load_lds_dwordx4 v[4:5], off
	s_add_i32 m0, s61, 0x2000
	s_mov_b64 s[14:15], 0x100
	global_load_lds_dwordx4 v[6:7], off
	v_lshl_add_u64 v[6:7], v[4:5], 0, s[14:15]
	s_add_i32 m0, s61, 0x4000
	s_mov_b64 s[24:25], 0x30000
	global_load_lds_dwordx4 v[6:7], off
	v_lshl_add_u64 v[6:7], v[4:5], 0, s[24:25]
	s_add_i32 m0, s61, 0x6000
	s_mov_b64 s[14:15], 0x30080
	global_load_lds_dwordx4 v[6:7], off
	v_lshl_add_u64 v[6:7], v[4:5], 0, s[14:15]
	s_add_i32 m0, s61, 0x8000
	s_mov_b64 s[14:15], 0x30100
	s_add_i32 s18, 0, 0x18000
	global_load_lds_dwordx4 v[6:7], off
	v_lshl_add_u64 v[6:7], v[4:5], 0, s[14:15]
	s_add_i32 m0, s61, 0xa000
	s_add_i32 s62, s18, s3
	global_load_lds_dwordx4 v[6:7], off
	s_mov_b32 m0, s62
	s_mov_b64 s[14:15], 0x10000
	global_load_lds_dwordx4 v[2:3], off
	v_lshl_add_u64 v[6:7], v[2:3], 0, s[14:15]
	s_add_i32 m0, s61, 0x1a000
	s_mov_b64 s[14:15], 0x60000
	global_load_lds_dwordx4 v[6:7], off
	s_waitcnt vmcnt(0) lgkmcnt(0)
	s_barrier
	v_lshl_add_u64 v[6:7], v[4:5], 0, s[14:15]
	s_add_i32 m0, s61, 0xc000
	s_mov_b64 s[14:15], 0x60080
	global_load_lds_dwordx4 v[6:7], off
	v_lshl_add_u64 v[6:7], v[4:5], 0, s[14:15]
	s_add_i32 m0, s61, 0xe000
	s_mov_b64 s[14:15], 0x60100
	global_load_lds_dwordx4 v[6:7], off
	v_lshl_add_u64 v[4:5], v[4:5], 0, s[14:15]
	s_add_i32 m0, s61, 0x10000
	s_mov_b64 s[14:15], 0x20000
	global_load_lds_dwordx4 v[4:5], off
	v_lshl_add_u64 v[4:5], v[2:3], 0, s[14:15]
	s_add_i32 m0, s61, 0x1c000
	v_lshl_add_u64 v[2:3], v[2:3], 0, s[24:25]
	global_load_lds_dwordx4 v[4:5], off
	s_add_i32 m0, s61, 0x1e000
	v_and_b32_e32 v163, 63, v58
	global_load_lds_dwordx4 v[2:3], off
	v_bitop3_b32 v2, v192, v8, 1 bitop3:0x78
	v_lshlrev_b32_e32 v3, 7, v191
	v_lshl_or_b32 v2, v2, 4, v3
	v_and_b32_e32 v3, 0x60, v161
	v_or_b32_e32 v197, v2, v3
	v_bitop3_b32 v198, v2, 32, v3 bitop3:0x36
	v_bitop3_b32 v199, v2, 64, v3 bitop3:0x36
	v_lshlrev_b32_e32 v3, 4, v58
	v_bitop3_b32 v200, v2, s75, v161 bitop3:0x34
	v_lshlrev_b32_e32 v2, 3, v163
	v_and_b32_e32 v3, 0xc0, v3
	v_lshlrev_b32_e32 v4, 1, v58
	s_and_b32 s3, s1, 0x3fffffc0
	v_and_or_b32 v3, v2, 24, v3
	v_and_b32_e32 v4, 32, v4
	v_and_b32_e32 v2, 0x100, v2
	s_lshl_b32 s3, s3, 2
	v_or3_b32 v193, v3, v4, v2
	v_add_u32_e32 v64, 0, v197
	v_add_u32_e32 v65, 0, v198
	v_add_u32_e32 v66, 0, v199
	ds_read_b128 v[2:5], v64 offset:0
	ds_read_b128 v[6:9], v64 offset:0x1000
	ds_read_b128 v[10:13], v65 offset:0
	ds_read_b128 v[14:17], v65 offset:0x1000
	ds_read_b128 v[50:53], v66 offset:0
	ds_read_b128 v[54:57], v66 offset:0x1000
	s_add_i32 s60, s3, 0
	s_mulk_i32 s11, 0x180
	s_mov_b32 s63, 3
	s_mov_b32 s24, 2
	s_add_i32 s60, s60, 0x24000
	s_mov_b32 s64, 1
	v_add_u32_e32 v196, s18, v193
	v_mov_b32_e32 v0, s11
	v_add_u32_e32 v67, 0, v200
	s_setprio 1
	s_waitcnt lgkmcnt(4)
	s_mov_b32 s40, 0
	s_waitcnt vmcnt(0) lgkmcnt(0)
	v_mfma_f32_32x32x16_bf16 v[34:49], v[2:5], v[142:145], 0
	ds_read_b128 v[2:5], v67 offset:0
	s_mov_b32 s41, s40
	s_mov_b32 s42, s40
	s_mov_b32 s43, s40
	s_mov_b32 s44, s40
	s_mov_b32 s45, s40
	s_mov_b32 s46, s40
	v_mfma_f32_32x32x16_bf16 v[18:33], v[6:9], v[142:145], 0
	ds_read_b128 v[6:9], v67 offset:0x1000
	s_waitcnt lgkmcnt(4)
	s_mov_b32 s47, s40
	s_mov_b32 s48, s40
	s_mov_b32 s49, s40
	s_mov_b32 s50, s40
	s_mov_b32 s51, s40
	v_mfma_f32_32x32x16_bf16 v[34:49], v[10:13], v[138:141], v[34:49]
	ds_read_b128 v[10:13], v64 offset:0x2000
	s_mov_b32 s52, s40
	s_mov_b32 s53, s40
	s_mov_b32 s54, s40
	s_mov_b32 s55, s40
	v_mfma_f32_32x32x16_bf16 v[18:33], v[14:17], v[138:141], v[18:33]
	ds_read_b128 v[14:17], v64 offset:0x3000
	s_waitcnt lgkmcnt(4)
	s_nop 0
	v_mfma_f32_32x32x16_bf16 v[34:49], v[50:53], v[134:137], v[34:49]
	ds_read_b128 v[50:53], v65 offset:0x2000
	v_mfma_f32_32x32x16_bf16 v[18:33], v[54:57], v[134:137], v[18:33]
	ds_read_b128 v[54:57], v65 offset:0x3000
	s_waitcnt lgkmcnt(4)
	s_nop 0
	v_mfma_f32_32x32x16_bf16 v[34:49], v[2:5], v[130:133], v[34:49]
	ds_read_b128 v[2:5], v66 offset:0x2000
	v_mfma_f32_32x32x16_bf16 v[18:33], v[6:9], v[130:133], v[18:33]
	ds_read_b128 v[6:9], v66 offset:0x3000
	s_waitcnt lgkmcnt(4)
	s_nop 0
	v_mfma_f32_32x32x16_bf16 v[34:49], v[10:13], v[126:129], v[34:49]
	ds_read_b128 v[10:13], v67 offset:0x2000
	v_mfma_f32_32x32x16_bf16 v[18:33], v[14:17], v[126:129], v[18:33]
	ds_read_b128 v[14:17], v67 offset:0x3000
	s_waitcnt lgkmcnt(4)
	s_nop 0
	v_mfma_f32_32x32x16_bf16 v[34:49], v[50:53], v[122:125], v[34:49]
	ds_read_b128 v[50:53], v64 offset:0x4000
	v_mfma_f32_32x32x16_bf16 v[18:33], v[54:57], v[122:125], v[18:33]
	ds_read_b128 v[54:57], v64 offset:0x5000
	s_waitcnt lgkmcnt(4)
	s_nop 0
	v_mfma_f32_32x32x16_bf16 v[34:49], v[2:5], v[118:121], v[34:49]
	ds_read_b128 v[2:5], v65 offset:0x4000
	v_mfma_f32_32x32x16_bf16 v[18:33], v[6:9], v[118:121], v[18:33]
	ds_read_b128 v[6:9], v65 offset:0x5000
	s_waitcnt lgkmcnt(4)
	s_nop 0
	v_mfma_f32_32x32x16_bf16 v[34:49], v[10:13], v[114:117], v[34:49]
	ds_read_b128 v[10:13], v66 offset:0x4000
	v_mfma_f32_32x32x16_bf16 v[18:33], v[14:17], v[114:117], v[18:33]
	ds_read_b128 v[14:17], v66 offset:0x5000
	s_waitcnt lgkmcnt(4)
	s_nop 0
	v_mfma_f32_32x32x16_bf16 v[34:49], v[50:53], v[110:113], v[34:49]
	ds_read_b128 v[50:53], v67 offset:0x4000
	v_mfma_f32_32x32x16_bf16 v[18:33], v[54:57], v[110:113], v[18:33]
	ds_read_b128 v[54:57], v67 offset:0x5000
	s_waitcnt lgkmcnt(4)
	s_waitcnt lgkmcnt(2)
	s_nop 0
	s_waitcnt lgkmcnt(0)
	v_mfma_f32_32x32x16_bf16 v[34:49], v[2:5], v[106:109], v[34:49]
	v_mfma_f32_32x32x16_bf16 v[18:33], v[6:9], v[106:109], v[18:33]
	v_mfma_f32_32x32x16_bf16 v[34:49], v[10:13], v[102:105], v[34:49]
	v_mfma_f32_32x32x16_bf16 v[18:33], v[14:17], v[102:105], v[18:33]
	v_mov_b64_e32 v[2:3], s[40:41]
	v_mov_b64_e32 v[4:5], s[42:43]
	v_mov_b64_e32 v[6:7], s[44:45]
	v_mov_b64_e32 v[8:9], s[46:47]
	v_mov_b64_e32 v[10:11], s[48:49]
	v_mov_b64_e32 v[12:13], s[50:51]
	v_mov_b64_e32 v[14:15], s[52:53]
	v_mfma_f32_32x32x16_bf16 v[34:49], v[50:53], v[98:101], v[34:49]
	v_mov_b64_e32 v[16:17], s[54:55]
	v_mfma_f32_32x32x16_bf16 v[18:33], v[54:57], v[98:101], v[18:33]
	s_setprio 0
	s_nop 8
	v_max_f32_e32 v50, v35, v35
	v_max_f32_e32 v51, v34, v34
	v_max_f32_e32 v50, v51, v50
	v_max3_f32 v50, v50, v36, v37
	v_max3_f32 v50, v50, v38, v39
	v_max3_f32 v50, v50, v40, v41
	v_max3_f32 v50, v50, v42, v43
	v_max3_f32 v50, v50, v44, v45
	v_max3_f32 v50, v50, v46, v47
	v_max3_f32 v50, v50, v48, v49
	v_max3_f32 v50, v50, v18, v19
	v_max3_f32 v50, v50, v20, v21
	v_max3_f32 v50, v50, v22, v23
	v_max3_f32 v50, v50, v24, v25
	v_max3_f32 v50, v50, v26, v27
	v_max3_f32 v50, v50, v28, v29
	v_max3_f32 v50, v50, v30, v31
	v_max3_f32 v50, v50, v32, v33
	v_mov_b32_e32 v51, v50
	s_nop 1
	v_permlane32_swap_b32_e32 v50, v51
	v_max_f32_e32 v51, v51, v51
	v_max_f32_e32 v50, v50, v50
	v_max_f32_e32 v50, v50, v51
	v_add_f32_e32 v51, 0x7149f2ca, v50
	v_max_f32_e32 v50, 0xf149f2ca, v50
	v_cmp_ge_f32_e32 vcc, s27, v51
	v_sub_f32_e32 v51, 0xf149f2ca, v50
	v_mul_f32_e32 v51, 0x3dd53b94, v51
	v_exp_f32_e32 v51, v51
	s_cmp_eq_u64 vcc, exec
	s_cselect_b64 vcc, -1, 0
	v_mov_b32_e32 v52, 0xf149f2ca
	v_cndmask_b32_e32 v202, v50, v52, vcc
	v_mul_f32_e32 v50, 0xbdd53b94, v202
	v_cndmask_b32_e64 v201, v51, 1.0, vcc
	v_mov_b32_e32 v51, v50
	v_fmamk_f32 v34, v34, 0x3dd53b94, v50
	v_fmamk_f32 v35, v35, 0x3dd53b94, v50
	v_fmamk_f32 v36, v36, 0x3dd53b94, v50
	v_fmamk_f32 v37, v37, 0x3dd53b94, v50
	v_fmamk_f32 v38, v38, 0x3dd53b94, v50
	v_fmamk_f32 v39, v39, 0x3dd53b94, v50
	v_fmamk_f32 v40, v40, 0x3dd53b94, v50
	v_fmamk_f32 v41, v41, 0x3dd53b94, v50
	v_fmamk_f32 v42, v42, 0x3dd53b94, v50
	v_fmamk_f32 v43, v43, 0x3dd53b94, v50
	v_fmamk_f32 v44, v44, 0x3dd53b94, v50
	v_fmamk_f32 v45, v45, 0x3dd53b94, v50
	v_fmamk_f32 v46, v46, 0x3dd53b94, v50
	v_fmamk_f32 v47, v47, 0x3dd53b94, v50
	v_fmamk_f32 v48, v48, 0x3dd53b94, v50
	v_fmac_f32_e32 v51, 0x3dd53b94, v49
	v_mad_i64_i32 v[164:165], s[14:15], v59, s20, v[0:1]
	v_bitop3_b32 v0, v60, 7, v58 bitop3:0x48
	v_pk_fma_f32 v[186:187], v[18:19], s[26:27], v[50:51] op_sel_hi:[1,0,0]
	v_exp_f32_e32 v216, v34
	v_exp_f32_e32 v218, v35
	v_exp_f32_e32 v214, v36
	v_exp_f32_e32 v217, v37
	v_exp_f32_e32 v212, v38
	v_exp_f32_e32 v215, v39
	v_exp_f32_e32 v211, v40
	v_exp_f32_e32 v213, v41
	v_exp_f32_e32 v208, v42
	v_exp_f32_e32 v210, v43
	v_exp_f32_e32 v206, v44
	v_exp_f32_e32 v209, v45
	v_exp_f32_e32 v204, v46
	v_exp_f32_e32 v207, v47
	v_exp_f32_e32 v203, v48
	v_exp_f32_e32 v205, v51
	v_lshl_or_b32 v164, v0, 4, v164
	v_or3_b32 v18, v62, s2, v61
	s_and_b32 s1, s1, 64
	v_and_b32_e32 v0, 32, v58
	v_ashrrev_i32_e32 v19, 31, v18
	v_or3_b32 v0, s1, v0, v63
	v_pk_fma_f32 v[172:173], v[32:33], s[26:27], v[50:51] op_sel_hi:[1,0,0]
	v_pk_fma_f32 v[174:175], v[30:31], s[26:27], v[50:51] op_sel_hi:[1,0,0]
	v_pk_fma_f32 v[176:177], v[28:29], s[26:27], v[50:51] op_sel_hi:[1,0,0]
	v_pk_fma_f32 v[178:179], v[26:27], s[26:27], v[50:51] op_sel_hi:[1,0,0]
	v_pk_fma_f32 v[180:181], v[24:25], s[26:27], v[50:51] op_sel_hi:[1,0,0]
	v_pk_fma_f32 v[182:183], v[22:23], s[26:27], v[50:51] op_sel_hi:[1,0,0]
	v_pk_fma_f32 v[184:185], v[20:21], s[26:27], v[50:51] op_sel_hi:[1,0,0]
	v_readlane_b32 s20, v254, 38
	v_lshlrev_b64 v[166:167], 11, v[18:19]
	v_lshlrev_b32_e32 v0, 1, v0
	v_mov_b64_e32 v[64:65], v[16:17]
	v_mov_b64_e32 v[48:49], v[16:17]
	v_mov_b64_e32 v[32:33], v[16:17]
	v_cmp_gt_u32_e64 s[36:37], 32, v163
	v_lshl_add_u32 v194, v191, 2, s60
	v_readlane_b32 s21, v254, 39
	v_or3_b32 v166, v166, s0, v0
	v_mov_b32_e32 v195, 0
	v_mov_b64_e32 v[62:63], v[14:15]
	v_mov_b64_e32 v[60:61], v[12:13]
	v_mov_b64_e32 v[58:59], v[10:11]
	v_mov_b64_e32 v[56:57], v[8:9]
	v_mov_b64_e32 v[54:55], v[6:7]
	v_mov_b64_e32 v[52:53], v[4:5]
	v_mov_b64_e32 v[50:51], v[2:3]
	v_mov_b64_e32 v[46:47], v[14:15]
	v_mov_b64_e32 v[44:45], v[12:13]
	v_mov_b64_e32 v[42:43], v[10:11]
	v_mov_b64_e32 v[40:41], v[8:9]
	v_mov_b64_e32 v[38:39], v[6:7]
	v_mov_b64_e32 v[36:37], v[4:5]
	v_mov_b64_e32 v[34:35], v[2:3]
	v_mov_b64_e32 v[30:31], v[14:15]
	v_mov_b64_e32 v[28:29], v[12:13]
	v_mov_b64_e32 v[26:27], v[10:11]
	v_mov_b64_e32 v[24:25], v[8:9]
	v_mov_b64_e32 v[22:23], v[6:7]
	v_mov_b64_e32 v[20:21], v[4:5]
	v_mov_b64_e32 v[18:19], v[2:3]
	s_mov_b32 s11, 1
.LBB2_333:
	v_lshl_add_u64 v[170:171], s[12:13], 0, v[164:165]
	s_mov_b64 s[0:1], 0xd090000
	v_lshl_add_u64 v[66:67], v[170:171], 0, s[0:1]
	s_mul_i32 s0, s63, 0x6000
	s_add_i32 s2, s61, s0
	s_mov_b32 m0, s2
	s_mov_b64 s[0:1], 0xd090080
	global_load_lds_dwordx4 v[66:67], off
	v_lshl_add_u64 v[66:67], v[170:171], 0, s[0:1]
	s_add_i32 m0, s2, 0x2000
	s_mov_b64 s[0:1], 0xd090100
	global_load_lds_dwordx4 v[66:67], off
	v_lshl_add_u64 v[66:67], v[170:171], 0, s[0:1]
	s_add_i32 m0, s2, 0x4000
	v_lshl_add_u64 v[168:169], s[12:13], 0, v[166:167]
	s_mov_b64 s[0:1], 0xe840000
	global_load_lds_dwordx4 v[66:67], off
	v_lshl_add_u64 v[66:67], v[168:169], 0, s[0:1]
	s_lshl_b32 s0, s24, 14
	s_add_i32 s2, s62, s0
	s_mov_b32 m0, s2
	s_mov_b64 s[0:1], 0xe850000
	global_load_lds_dwordx4 v[66:67], off
	v_lshl_add_u64 v[66:67], v[168:169], 0, s[0:1]
	s_add_i32 m0, s2, 0x2000
	s_nop 0
	global_load_lds_dwordx4 v[66:67], off
	s_mul_i32 s0, s64, 0x6000
	s_add_i32 s0, s0, 0
	v_add_u32_e32 v0, s0, v197
	v_add_u32_e32 v156, s0, v198
	v_add_u32_e32 v157, s0, v199
	ds_read_b128 v[66:69], v0 offset:0
	ds_read_b128 v[70:73], v0 offset:0x1000
	ds_read_b128 v[220:223], v156 offset:0
	ds_read_b128 v[224:227], v156 offset:0x1000
	ds_read_b128 v[228:231], v157 offset:0
	ds_read_b128 v[232:235], v157 offset:0x1000
	v_add_u32_e32 v158, s0, v200
	s_setprio 1
	s_waitcnt lgkmcnt(4)
	ds_read_b128 v[236:239], v158 offset:0
	ds_read_b128 v[240:243], v158 offset:0x1000
	s_waitcnt lgkmcnt(4)
	s_nop 0
	v_mfma_f32_32x32x16_bf16 v[82:97], v[66:69], v[142:145], 0
	v_mfma_f32_32x32x16_bf16 v[66:81], v[70:73], v[142:145], 0
	v_mfma_f32_32x32x16_bf16 v[82:97], v[220:223], v[138:141], v[82:97]
	ds_read_b128 v[220:223], v0 offset:0x2000
	v_mfma_f32_32x32x16_bf16 v[66:81], v[224:227], v[138:141], v[66:81]
	ds_read_b128 v[224:227], v0 offset:0x3000
	s_waitcnt lgkmcnt(4)
	s_nop 0
	v_mfma_f32_32x32x16_bf16 v[82:97], v[228:231], v[134:137], v[82:97]
	ds_read_b128 v[228:231], v156 offset:0x2000
	v_mfma_f32_32x32x16_bf16 v[66:81], v[232:235], v[134:137], v[66:81]
	ds_read_b128 v[232:235], v156 offset:0x3000
	s_waitcnt lgkmcnt(4)
	s_nop 0
	v_mfma_f32_32x32x16_bf16 v[82:97], v[236:239], v[130:133], v[82:97]
	ds_read_b128 v[236:239], v157 offset:0x2000
	v_mfma_f32_32x32x16_bf16 v[66:81], v[240:243], v[130:133], v[66:81]
	ds_read_b128 v[240:243], v157 offset:0x3000
	s_waitcnt lgkmcnt(4)
	s_nop 0
	v_mfma_f32_32x32x16_bf16 v[82:97], v[220:223], v[126:129], v[82:97]
	ds_read_b128 v[220:223], v158 offset:0x2000
	v_mfma_f32_32x32x16_bf16 v[66:81], v[224:227], v[126:129], v[66:81]
	ds_read_b128 v[224:227], v158 offset:0x3000
	s_waitcnt lgkmcnt(4)
	s_nop 0
	v_mfma_f32_32x32x16_bf16 v[82:97], v[228:231], v[122:125], v[82:97]
	ds_read_b128 v[228:231], v0 offset:0x4000
	v_mfma_f32_32x32x16_bf16 v[66:81], v[232:235], v[122:125], v[66:81]
	ds_read_b128 v[232:235], v0 offset:0x5000
	s_waitcnt lgkmcnt(4)
	s_nop 0
	v_mfma_f32_32x32x16_bf16 v[82:97], v[236:239], v[118:121], v[82:97]
	ds_read_b128 v[236:239], v156 offset:0x4000
	v_mfma_f32_32x32x16_bf16 v[66:81], v[240:243], v[118:121], v[66:81]
	ds_read_b128 v[240:243], v156 offset:0x5000
	s_waitcnt lgkmcnt(4)
	s_nop 0
	v_mfma_f32_32x32x16_bf16 v[82:97], v[220:223], v[114:117], v[82:97]
	ds_read_b128 v[220:223], v157 offset:0x4000
	v_mfma_f32_32x32x16_bf16 v[66:81], v[224:227], v[114:117], v[66:81]
	ds_read_b128 v[224:227], v157 offset:0x5000
	s_waitcnt lgkmcnt(4)
	s_nop 0
	v_mfma_f32_32x32x16_bf16 v[82:97], v[228:231], v[110:113], v[82:97]
	ds_read_b128 v[228:231], v158 offset:0x4000
	v_mfma_f32_32x32x16_bf16 v[66:81], v[232:235], v[110:113], v[66:81]
	ds_read_b128 v[232:235], v158 offset:0x5000
	s_waitcnt lgkmcnt(4)
	s_waitcnt lgkmcnt(2)
	s_nop 0
	s_waitcnt lgkmcnt(0)
	v_mfma_f32_32x32x16_bf16 v[82:97], v[236:239], v[106:109], v[82:97]
	v_mfma_f32_32x32x16_bf16 v[66:81], v[240:243], v[106:109], v[66:81]
	v_mfma_f32_32x32x16_bf16 v[82:97], v[220:223], v[102:105], v[82:97]
	v_mfma_f32_32x32x16_bf16 v[66:81], v[224:227], v[102:105], v[66:81]
	v_mfma_f32_32x32x16_bf16 v[82:97], v[228:231], v[98:101], v[82:97]
	v_mfma_f32_32x32x16_bf16 v[66:81], v[232:235], v[98:101], v[66:81]
	s_setprio 0
	v_exp_f32_e32 v224, v172
	v_add_f32_e32 v172, 0, v216
	v_add_f32_e32 v172, v218, v172
	v_add_f32_e32 v172, v214, v172
	v_add_f32_e32 v172, v217, v172
	v_add_f32_e32 v172, v212, v172
	v_add_f32_e32 v172, v215, v172
	v_add_f32_e32 v172, v211, v172
	v_add_f32_e32 v172, v213, v172
	v_add_f32_e32 v172, v208, v172
	v_add_f32_e32 v172, v210, v172
	v_add_f32_e32 v172, v206, v172
	v_add_f32_e32 v172, v209, v172
	v_exp_f32_e32 v0, v186
	v_add_f32_e32 v172, v204, v172
	v_exp_f32_e32 v156, v187
	v_add_f32_e32 v172, v207, v172
	v_exp_f32_e32 v157, v184
	v_add_f32_e32 v172, v203, v172
	v_exp_f32_e32 v158, v185
	v_add_f32_e32 v172, v205, v172
	v_exp_f32_e32 v159, v182
	v_add_f32_e32 v172, v0, v172
	v_exp_f32_e32 v184, v183
	v_add_f32_e32 v172, v156, v172
	v_exp_f32_e32 v185, v180
	v_add_f32_e32 v172, v157, v172
	v_exp_f32_e32 v186, v181
	v_add_f32_e32 v172, v158, v172
	v_exp_f32_e32 v187, v178
	v_add_f32_e32 v172, v159, v172
	v_exp_f32_e32 v219, v179
	v_add_f32_e32 v172, v184, v172
	v_exp_f32_e32 v220, v176
	v_add_f32_e32 v172, v185, v172
	v_exp_f32_e32 v221, v177
	v_add_f32_e32 v172, v186, v172
	v_exp_f32_e32 v222, v174
	v_add_f32_e32 v172, v187, v172
	v_exp_f32_e32 v223, v175
	v_add_f32_e32 v172, v219, v172
	v_add_f32_e32 v172, v220, v172
	v_exp_f32_e32 v225, v173
	v_add_f32_e32 v172, v221, v172
	v_add_f32_e32 v172, v222, v172
	v_add_f32_e32 v172, v223, v172
	v_add_f32_e32 v172, v224, v172
	v_add_f32_e32 v172, v225, v172
	v_mov_b32_e32 v173, v172
	v_cvt_pk_bf16_f32 v174, v216, v218
	v_cvt_pk_bf16_f32 v175, v214, v217
	v_cvt_pk_bf16_f32 v176, v212, v215
	s_nop 1
	v_permlane32_swap_b32_e32 v172, v173
	v_cvt_pk_bf16_f32 v177, v211, v213
	v_permlane32_swap_b32_e32 v174, v176
	v_cvt_pk_bf16_f32 v178, v208, v210
	v_cvt_pk_bf16_f32 v179, v206, v209
	v_cvt_pk_bf16_f32 v180, v204, v207
	v_cvt_pk_bf16_f32 v181, v203, v205
	v_cvt_pk_bf16_f32 v182, v0, v156
	v_cvt_pk_bf16_f32 v183, v157, v158
	v_cvt_pk_bf16_f32 v184, v159, v184
	v_cvt_pk_bf16_f32 v185, v185, v186
	v_cvt_pk_bf16_f32 v204, v187, v219
	v_cvt_pk_bf16_f32 v205, v220, v221
	v_cvt_pk_bf16_f32 v206, v222, v223
	v_cvt_pk_bf16_f32 v207, v224, v225
	v_permlane32_swap_b32_e32 v175, v177
	v_permlane32_swap_b32_e32 v178, v180
	v_permlane32_swap_b32_e32 v179, v181
	v_permlane32_swap_b32_e32 v182, v184
	v_permlane32_swap_b32_e32 v183, v185
	v_permlane32_swap_b32_e32 v204, v206
	v_permlane32_swap_b32_e32 v205, v207
	v_lshl_add_u32 v0, s40, 14, v196
	ds_read_b64_tr_b16 v[208:209], v0 offset:0
	ds_read_b64_tr_b16 v[210:211], v0 offset:0x800
	ds_read_b64_tr_b16 v[212:213], v0 offset:0x1000
	ds_read_b64_tr_b16 v[214:215], v0 offset:0x1800
	ds_read_b64_tr_b16 v[216:217], v0 offset:0x2000
	ds_read_b64_tr_b16 v[218:219], v0 offset:0x2800
	ds_read_b64_tr_b16 v[220:221], v0 offset:0x3000
	ds_read_b64_tr_b16 v[222:223], v0 offset:0x3800
	s_waitcnt lgkmcnt(0)
	s_nop 0
	v_mfma_f32_32x32x16_bf16 v[2:17], v[174:177], v[208:211], v[2:17]
	ds_read_b64_tr_b16 v[208:209], v0 offset:0x200
	ds_read_b64_tr_b16 v[210:211], v0 offset:0xa00
	v_mfma_f32_32x32x16_bf16 v[2:17], v[178:181], v[212:215], v[2:17]
	ds_read_b64_tr_b16 v[212:213], v0 offset:0x1200
	ds_read_b64_tr_b16 v[214:215], v0 offset:0x1a00
	v_mfma_f32_32x32x16_bf16 v[2:17], v[182:185], v[216:219], v[2:17]
	ds_read_b64_tr_b16 v[216:217], v0 offset:0x2200
	ds_read_b64_tr_b16 v[218:219], v0 offset:0x2a00
	v_mfma_f32_32x32x16_bf16 v[2:17], v[204:207], v[220:223], v[2:17]
	ds_read_b64_tr_b16 v[220:221], v0 offset:0x3200
	ds_read_b64_tr_b16 v[222:223], v0 offset:0x3a00
	s_waitcnt lgkmcnt(0)
	v_mfma_f32_32x32x16_bf16 v[50:65], v[174:177], v[208:211], v[50:65]
	ds_read_b64_tr_b16 v[208:209], v0 offset:0x400
	ds_read_b64_tr_b16 v[210:211], v0 offset:0xc00
	v_mfma_f32_32x32x16_bf16 v[50:65], v[178:181], v[212:215], v[50:65]
	ds_read_b64_tr_b16 v[212:213], v0 offset:0x1400
	ds_read_b64_tr_b16 v[214:215], v0 offset:0x1c00
	v_mfma_f32_32x32x16_bf16 v[50:65], v[182:185], v[216:219], v[50:65]
	ds_read_b64_tr_b16 v[216:217], v0 offset:0x2400
	ds_read_b64_tr_b16 v[218:219], v0 offset:0x2c00
	v_mfma_f32_32x32x16_bf16 v[50:65], v[204:207], v[220:223], v[50:65]
	ds_read_b64_tr_b16 v[220:221], v0 offset:0x3400
	ds_read_b64_tr_b16 v[222:223], v0 offset:0x3c00
	s_waitcnt lgkmcnt(0)
	v_mfma_f32_32x32x16_bf16 v[34:49], v[174:177], v[208:211], v[34:49]
	ds_read_b64_tr_b16 v[208:209], v0 offset:0x600
	ds_read_b64_tr_b16 v[210:211], v0 offset:0xe00
	v_mfma_f32_32x32x16_bf16 v[34:49], v[178:181], v[212:215], v[34:49]
	ds_read_b64_tr_b16 v[212:213], v0 offset:0x1600
	ds_read_b64_tr_b16 v[214:215], v0 offset:0x1e00
	v_mfma_f32_32x32x16_bf16 v[34:49], v[182:185], v[216:219], v[34:49]
	ds_read_b64_tr_b16 v[216:217], v0 offset:0x2600
	ds_read_b64_tr_b16 v[218:219], v0 offset:0x2e00
	v_mfma_f32_32x32x16_bf16 v[34:49], v[204:207], v[220:223], v[34:49]
	ds_read_b64_tr_b16 v[220:221], v0 offset:0x3600
	ds_read_b64_tr_b16 v[222:223], v0 offset:0x3e00
	s_waitcnt lgkmcnt(0)
	v_mfma_f32_32x32x16_bf16 v[18:33], v[174:177], v[208:211], v[18:33]
	v_max_f32_e32 v0, v83, v83
	v_max_f32_e32 v156, v82, v82
	v_max_f32_e32 v0, v156, v0
	v_max3_f32 v0, v0, v84, v85
	v_max3_f32 v0, v0, v86, v87
	v_max3_f32 v0, v0, v88, v89
	v_max3_f32 v0, v0, v90, v91
	v_max3_f32 v0, v0, v92, v93
	v_max3_f32 v0, v0, v94, v95
	v_mfma_f32_32x32x16_bf16 v[18:33], v[178:181], v[212:215], v[18:33]
	v_max3_f32 v0, v0, v96, v97
	v_max3_f32 v0, v0, v66, v67
	v_max3_f32 v0, v0, v68, v69
	v_max3_f32 v0, v0, v70, v71
	v_max3_f32 v0, v0, v72, v73
	v_max3_f32 v0, v0, v74, v75
	v_max3_f32 v0, v0, v76, v77
	v_max3_f32 v0, v0, v78, v79
	v_mfma_f32_32x32x16_bf16 v[18:33], v[182:185], v[216:219], v[18:33]
	v_max3_f32 v0, v0, v80, v81
	v_mov_b32_e32 v156, v0
	s_nop 1
	v_permlane32_swap_b32_e32 v0, v156
	v_max_f32_e32 v156, v156, v156
	v_max_f32_e32 v0, v0, v0
	v_max_f32_e32 v0, v0, v156
	v_sub_f32_e32 v156, v0, v202
	v_cmp_ge_f32_e32 vcc, s27, v156
	v_max_f32_e32 v156, v202, v202
	v_max_f32_e32 v0, v156, v0
	v_mfma_f32_32x32x16_bf16 v[18:33], v[204:207], v[220:223], v[18:33]
	v_sub_f32_e32 v156, v202, v0
	v_mul_f32_e32 v156, 0x3dd53b94, v156
	v_exp_f32_e32 v156, v156
	s_cmp_eq_u64 vcc, exec
	s_cselect_b64 s[0:1], -1, 0
	v_cndmask_b32_e64 v174, v156, 1.0, s[0:1]
	v_cmp_gt_f32_e32 vcc, 1.0, v174
	s_cbranch_vccz .LBB2_337
	s_and_saveexec_b64 s[2:3], s[36:37]
	ds_write_b32 v194, v174 offset:128
	s_or_b64 exec, exec, s[2:3]
	s_waitcnt lgkmcnt(0)
	v_add_u32_e32 v156, s60, v162
	ds_read_b128 v[176:179], v156 offset:224
	ds_read_b128 v[180:183], v156 offset:192
	ds_read_b128 v[184:187], v156 offset:160
	ds_read_b128 v[204:207], v156 offset:128
	s_waitcnt lgkmcnt(0)
	v_pk_mul_f32 v[14:15], v[14:15], v[176:177]
	v_pk_mul_f32 v[10:11], v[10:11], v[180:181]
	v_pk_mul_f32 v[6:7], v[6:7], v[184:185]
	v_pk_mul_f32 v[16:17], v[16:17], v[178:179]
	v_pk_mul_f32 v[12:13], v[12:13], v[182:183]
	v_pk_mul_f32 v[8:9], v[8:9], v[186:187]
	v_pk_mul_f32 v[4:5], v[4:5], v[206:207]
	v_pk_mul_f32 v[2:3], v[2:3], v[204:205]
	v_pk_mul_f32 v[62:63], v[62:63], v[176:177]
	v_pk_mul_f32 v[58:59], v[58:59], v[180:181]
	v_pk_mul_f32 v[54:55], v[54:55], v[184:185]
	v_pk_mul_f32 v[64:65], v[64:65], v[178:179]
	v_pk_mul_f32 v[60:61], v[60:61], v[182:183]
	v_pk_mul_f32 v[56:57], v[56:57], v[186:187]
	v_pk_mul_f32 v[52:53], v[52:53], v[206:207]
	v_pk_mul_f32 v[50:51], v[50:51], v[204:205]
	v_pk_mul_f32 v[46:47], v[46:47], v[176:177]
	v_pk_mul_f32 v[42:43], v[42:43], v[180:181]
	v_pk_mul_f32 v[38:39], v[38:39], v[184:185]
	v_pk_mul_f32 v[48:49], v[48:49], v[178:179]
	v_pk_mul_f32 v[44:45], v[44:45], v[182:183]
	v_pk_mul_f32 v[40:41], v[40:41], v[186:187]
	v_pk_mul_f32 v[36:37], v[36:37], v[206:207]
	v_pk_mul_f32 v[34:35], v[34:35], v[204:205]
	v_pk_mul_f32 v[30:31], v[30:31], v[176:177]
	v_pk_mul_f32 v[26:27], v[26:27], v[180:181]
	v_pk_mul_f32 v[22:23], v[22:23], v[184:185]
	v_pk_mul_f32 v[32:33], v[32:33], v[178:179]
	v_pk_mul_f32 v[28:29], v[28:29], v[182:183]
	v_pk_mul_f32 v[24:25], v[24:25], v[186:187]
	v_pk_mul_f32 v[20:21], v[20:21], v[206:207]
	v_pk_mul_f32 v[18:19], v[18:19], v[204:205]
.LBB2_337:
	s_waitcnt vmcnt(5) lgkmcnt(0)
	s_barrier
	s_cmpk_gt_u32 s11, 0x7c
	s_cselect_b64 s[18:19], -1, 0
	s_and_b64 vcc, exec, s[18:19]
	s_cbranch_vccnz .LBB2_339
	s_add_i32 s2, s63, 1
	s_and_b32 s14, s2, 3
	s_mulk_i32 s14, 0x6000
	s_mov_b64 s[2:3], 0xd0c0000
	s_add_i32 s14, s61, s14
	v_lshl_add_u64 v[156:157], v[170:171], 0, s[2:3]
	s_mov_b32 m0, s14
	s_mov_b64 s[2:3], 0xd0c0080
	global_load_lds_dwordx4 v[156:157], off
	v_lshl_add_u64 v[156:157], v[170:171], 0, s[2:3]
	s_add_i32 m0, s14, 0x2000
	s_mov_b64 s[2:3], 0xd0c0100
	global_load_lds_dwordx4 v[156:157], off
	v_lshl_add_u64 v[156:157], v[170:171], 0, s[2:3]
	s_add_i32 m0, s14, 0x4000
	s_nop 0
	global_load_lds_dwordx4 v[156:157], off
.LBB2_339:
	s_add_i32 s2, s64, 1
	s_and_b32 s2, s2, 3
	s_add_i32 s3, s40, 1
	s_cmp_lg_u32 s40, 2
	s_cselect_b32 s25, s3, 0
	s_add_i32 s3, s24, 1
	s_cmp_lg_u32 s24, 2
	v_cndmask_b32_e64 v0, v0, v202, s[0:1]
	s_cselect_b32 s24, s3, 0
	v_mul_f32_e32 v180, 0xbdd53b94, v0
	s_mov_b64 s[0:1], 0xe860000
	v_fmamk_f32 v204, v66, 0x3dd53b94, v180
	v_fmamk_f32 v205, v67, 0x3dd53b94, v180
	v_lshl_add_u64 v[66:67], v[168:169], 0, s[0:1]
	s_lshl_b32 s0, s24, 14
	s_add_i32 s3, s62, s0
	s_mov_b32 m0, s3
	s_mov_b64 s[0:1], 0xe870000
	global_load_lds_dwordx4 v[66:67], off
	v_lshl_add_u64 v[66:67], v[168:169], 0, s[0:1]
	s_add_i32 m0, s3, 0x2000
	v_fmamk_f32 v90, v90, 0x3dd53b94, v180
	global_load_lds_dwordx4 v[66:67], off
	v_exp_f32_e32 v170, v90
	v_fmamk_f32 v82, v82, 0x3dd53b94, v180
	v_fmamk_f32 v83, v83, 0x3dd53b94, v180
	v_fmamk_f32 v84, v84, 0x3dd53b94, v180
	v_fmamk_f32 v85, v85, 0x3dd53b94, v180
	v_fmamk_f32 v86, v86, 0x3dd53b94, v180
	v_fmamk_f32 v87, v87, 0x3dd53b94, v180
	v_fmamk_f32 v88, v88, 0x3dd53b94, v180
	v_fmamk_f32 v89, v89, 0x3dd53b94, v180
	v_fmamk_f32 v91, v91, 0x3dd53b94, v180
	v_fmamk_f32 v92, v92, 0x3dd53b94, v180
	v_fmamk_f32 v93, v93, 0x3dd53b94, v180
	v_fmamk_f32 v94, v94, 0x3dd53b94, v180
	v_fmamk_f32 v95, v95, 0x3dd53b94, v180
	v_fmamk_f32 v96, v96, 0x3dd53b94, v180
	v_fmamk_f32 v97, v97, 0x3dd53b94, v180
	v_fmamk_f32 v206, v68, 0x3dd53b94, v180
	v_fmamk_f32 v207, v69, 0x3dd53b94, v180
	v_fmamk_f32 v208, v70, 0x3dd53b94, v180
	v_fmamk_f32 v209, v71, 0x3dd53b94, v180
	v_fmamk_f32 v210, v72, 0x3dd53b94, v180
	v_fmamk_f32 v211, v73, 0x3dd53b94, v180
	v_fmamk_f32 v212, v74, 0x3dd53b94, v180
	v_fmamk_f32 v213, v75, 0x3dd53b94, v180
	v_fmamk_f32 v214, v76, 0x3dd53b94, v180
	v_fmamk_f32 v215, v77, 0x3dd53b94, v180
	v_fmamk_f32 v216, v78, 0x3dd53b94, v180
	v_fmamk_f32 v217, v79, 0x3dd53b94, v180
	v_fmamk_f32 v218, v80, 0x3dd53b94, v180
	v_fmac_f32_e32 v180, 0x3dd53b94, v81
	v_exp_f32_e32 v182, v82
	v_exp_f32_e32 v183, v83
	v_exp_f32_e32 v184, v84
	v_exp_f32_e32 v185, v85
	v_exp_f32_e32 v186, v86
	v_exp_f32_e32 v187, v87
	v_exp_f32_e32 v202, v88
	v_exp_f32_e32 v203, v89
	v_exp_f32_e32 v171, v91
	v_exp_f32_e32 v175, v92
	v_exp_f32_e32 v176, v93
	v_exp_f32_e32 v177, v94
	v_exp_f32_e32 v178, v95
	v_exp_f32_e32 v179, v96
	v_exp_f32_e32 v181, v97
	s_mulk_i32 s2, 0x6000
	s_add_i32 s0, s2, 0
	v_add_u32_e32 v156, s0, v197
	v_add_u32_e32 v157, s0, v198
	v_add_u32_e32 v158, s0, v199
	ds_read_b128 v[66:69], v156 offset:0
	ds_read_b128 v[70:73], v156 offset:0x1000
	ds_read_b128 v[220:223], v157 offset:0
	ds_read_b128 v[224:227], v157 offset:0x1000
	ds_read_b128 v[228:231], v158 offset:0
	ds_read_b128 v[232:235], v158 offset:0x1000
	v_add_u32_e32 v159, s0, v200
	s_setprio 1
	s_waitcnt lgkmcnt(4)
	ds_read_b128 v[236:239], v159 offset:0
	ds_read_b128 v[240:243], v159 offset:0x1000
	s_waitcnt lgkmcnt(4)
	s_nop 0
	v_mfma_f32_32x32x16_bf16 v[82:97], v[66:69], v[142:145], 0
	v_mfma_f32_32x32x16_bf16 v[66:81], v[70:73], v[142:145], 0
	v_mfma_f32_32x32x16_bf16 v[82:97], v[220:223], v[138:141], v[82:97]
	ds_read_b128 v[220:223], v156 offset:0x2000
	v_mfma_f32_32x32x16_bf16 v[66:81], v[224:227], v[138:141], v[66:81]
	ds_read_b128 v[224:227], v156 offset:0x3000
	s_waitcnt lgkmcnt(4)
	s_nop 0
	v_mfma_f32_32x32x16_bf16 v[82:97], v[228:231], v[134:137], v[82:97]
	ds_read_b128 v[228:231], v157 offset:0x2000
	v_mfma_f32_32x32x16_bf16 v[66:81], v[232:235], v[134:137], v[66:81]
	ds_read_b128 v[232:235], v157 offset:0x3000
	s_waitcnt lgkmcnt(4)
	s_nop 0
	v_mfma_f32_32x32x16_bf16 v[82:97], v[236:239], v[130:133], v[82:97]
	ds_read_b128 v[236:239], v158 offset:0x2000
	v_mfma_f32_32x32x16_bf16 v[66:81], v[240:243], v[130:133], v[66:81]
	ds_read_b128 v[240:243], v158 offset:0x3000
	s_waitcnt lgkmcnt(4)
	s_nop 0
	v_mfma_f32_32x32x16_bf16 v[82:97], v[220:223], v[126:129], v[82:97]
	ds_read_b128 v[220:223], v159 offset:0x2000
	v_mfma_f32_32x32x16_bf16 v[66:81], v[224:227], v[126:129], v[66:81]
	ds_read_b128 v[224:227], v159 offset:0x3000
	s_waitcnt lgkmcnt(4)
	s_nop 0
	v_mfma_f32_32x32x16_bf16 v[82:97], v[228:231], v[122:125], v[82:97]
	ds_read_b128 v[228:231], v156 offset:0x4000
	v_mfma_f32_32x32x16_bf16 v[66:81], v[232:235], v[122:125], v[66:81]
	ds_read_b128 v[232:235], v156 offset:0x5000
	s_waitcnt lgkmcnt(4)
	s_nop 0
	v_mfma_f32_32x32x16_bf16 v[82:97], v[236:239], v[118:121], v[82:97]
	ds_read_b128 v[236:239], v157 offset:0x4000
	v_mfma_f32_32x32x16_bf16 v[66:81], v[240:243], v[118:121], v[66:81]
	ds_read_b128 v[240:243], v157 offset:0x5000
	s_waitcnt lgkmcnt(4)
	s_nop 0
	v_mfma_f32_32x32x16_bf16 v[82:97], v[220:223], v[114:117], v[82:97]
	ds_read_b128 v[220:223], v158 offset:0x4000
	v_mfma_f32_32x32x16_bf16 v[66:81], v[224:227], v[114:117], v[66:81]
	ds_read_b128 v[224:227], v158 offset:0x5000
	s_waitcnt lgkmcnt(4)
	s_nop 0
	v_mfma_f32_32x32x16_bf16 v[82:97], v[228:231], v[110:113], v[82:97]
	ds_read_b128 v[228:231], v159 offset:0x4000
	v_mfma_f32_32x32x16_bf16 v[66:81], v[232:235], v[110:113], v[66:81]
	ds_read_b128 v[232:235], v159 offset:0x5000
	s_waitcnt lgkmcnt(4)
	s_waitcnt lgkmcnt(2)
	s_nop 0
	s_waitcnt lgkmcnt(0)
	v_mfma_f32_32x32x16_bf16 v[82:97], v[236:239], v[106:109], v[82:97]
	v_mfma_f32_32x32x16_bf16 v[66:81], v[240:243], v[106:109], v[66:81]
	v_mfma_f32_32x32x16_bf16 v[82:97], v[220:223], v[102:105], v[82:97]
	v_mfma_f32_32x32x16_bf16 v[66:81], v[224:227], v[102:105], v[66:81]
	v_mfma_f32_32x32x16_bf16 v[82:97], v[228:231], v[98:101], v[82:97]
	v_mfma_f32_32x32x16_bf16 v[66:81], v[232:235], v[98:101], v[66:81]
	s_setprio 0
	v_add_f32_e32 v169, 0, v182
	v_add_f32_e32 v169, v183, v169
	v_add_f32_e32 v169, v184, v169
	v_add_f32_e32 v169, v185, v169
	v_add_f32_e32 v169, v186, v169
	v_add_f32_e32 v169, v187, v169
	v_add_f32_e32 v169, v202, v169
	v_add_f32_e32 v169, v203, v169
	v_add_f32_e32 v169, v170, v169
	v_add_f32_e32 v169, v171, v169
	v_add_f32_e32 v169, v175, v169
	v_add_f32_e32 v169, v176, v169
	v_exp_f32_e32 v156, v204
	v_add_f32_e32 v169, v177, v169
	v_exp_f32_e32 v157, v205
	v_add_f32_e32 v169, v178, v169
	v_exp_f32_e32 v158, v206
	v_add_f32_e32 v169, v179, v169
	v_exp_f32_e32 v159, v207
	v_add_f32_e32 v169, v181, v169
	v_exp_f32_e32 v168, v208
	v_add_f32_e32 v169, v156, v169
	v_exp_f32_e32 v206, v209
	v_add_f32_e32 v169, v157, v169
	v_exp_f32_e32 v207, v210
	v_add_f32_e32 v169, v158, v169
	v_exp_f32_e32 v208, v211
	v_add_f32_e32 v169, v159, v169
	v_exp_f32_e32 v209, v212
	v_add_f32_e32 v169, v168, v169
	v_exp_f32_e32 v210, v213
	v_add_f32_e32 v169, v206, v169
	v_exp_f32_e32 v211, v214
	v_add_f32_e32 v169, v207, v169
	v_exp_f32_e32 v212, v215
	v_add_f32_e32 v169, v208, v169
	v_exp_f32_e32 v213, v216
	v_add_f32_e32 v169, v209, v169
	v_exp_f32_e32 v214, v217
	v_add_f32_e32 v169, v210, v169
	v_exp_f32_e32 v215, v218
	v_add_f32_e32 v169, v211, v169
	v_exp_f32_e32 v216, v180
	v_add_f32_e32 v169, v212, v169
	v_add_f32_e32 v169, v213, v169
	v_add_f32_e32 v169, v214, v169
	v_add_f32_e32 v169, v215, v169
	v_add_f32_e32 v169, v216, v169
	v_mov_b32_e32 v180, v169
	s_nop 1
	v_permlane32_swap_b32_e32 v169, v180
	v_cvt_pk_bf16_f32 v182, v182, v183
	v_cvt_pk_bf16_f32 v183, v184, v185
	v_cvt_pk_bf16_f32 v184, v186, v187
	v_cvt_pk_bf16_f32 v185, v202, v203
	v_cvt_pk_bf16_f32 v202, v170, v171
	v_cvt_pk_bf16_f32 v203, v175, v176
	v_cvt_pk_bf16_f32 v204, v177, v178
	v_cvt_pk_bf16_f32 v205, v179, v181
	v_cvt_pk_bf16_f32 v176, v156, v157
	v_cvt_pk_bf16_f32 v177, v158, v159
	v_cvt_pk_bf16_f32 v178, v168, v206
	v_cvt_pk_bf16_f32 v179, v207, v208
	v_cvt_pk_bf16_f32 v206, v209, v210
	v_cvt_pk_bf16_f32 v207, v211, v212
	v_cvt_pk_bf16_f32 v208, v213, v214
	v_cvt_pk_bf16_f32 v209, v215, v216
	s_nop 0
	v_permlane32_swap_b32_e32 v182, v184
	v_permlane32_swap_b32_e32 v183, v185
	v_permlane32_swap_b32_e32 v202, v204
	v_permlane32_swap_b32_e32 v203, v205
	v_permlane32_swap_b32_e32 v176, v178
	v_permlane32_swap_b32_e32 v177, v179
	v_permlane32_swap_b32_e32 v206, v208
	v_permlane32_swap_b32_e32 v207, v209
	v_lshl_add_u32 v156, s25, 14, v196
	ds_read_b64_tr_b16 v[210:211], v156 offset:0
	ds_read_b64_tr_b16 v[212:213], v156 offset:0x800
	ds_read_b64_tr_b16 v[214:215], v156 offset:0x1000
	ds_read_b64_tr_b16 v[216:217], v156 offset:0x1800
	ds_read_b64_tr_b16 v[218:219], v156 offset:0x2000
	ds_read_b64_tr_b16 v[220:221], v156 offset:0x2800
	ds_read_b64_tr_b16 v[222:223], v156 offset:0x3000
	ds_read_b64_tr_b16 v[224:225], v156 offset:0x3800
	s_waitcnt lgkmcnt(0)
	s_nop 0
	v_mfma_f32_32x32x16_bf16 v[2:17], v[182:185], v[210:213], v[2:17]
	ds_read_b64_tr_b16 v[210:211], v156 offset:0x200
	ds_read_b64_tr_b16 v[212:213], v156 offset:0xa00
	v_mfma_f32_32x32x16_bf16 v[2:17], v[202:205], v[214:217], v[2:17]
	ds_read_b64_tr_b16 v[214:215], v156 offset:0x1200
	ds_read_b64_tr_b16 v[216:217], v156 offset:0x1a00
	v_mfma_f32_32x32x16_bf16 v[2:17], v[176:179], v[218:221], v[2:17]
	ds_read_b64_tr_b16 v[218:219], v156 offset:0x2200
	ds_read_b64_tr_b16 v[220:221], v156 offset:0x2a00
	v_mfma_f32_32x32x16_bf16 v[2:17], v[206:209], v[222:225], v[2:17]
	ds_read_b64_tr_b16 v[222:223], v156 offset:0x3200
	ds_read_b64_tr_b16 v[224:225], v156 offset:0x3a00
	s_waitcnt lgkmcnt(0)
	v_mfma_f32_32x32x16_bf16 v[50:65], v[182:185], v[210:213], v[50:65]
	ds_read_b64_tr_b16 v[210:211], v156 offset:0x400
	ds_read_b64_tr_b16 v[212:213], v156 offset:0xc00
	v_mfma_f32_32x32x16_bf16 v[50:65], v[202:205], v[214:217], v[50:65]
	ds_read_b64_tr_b16 v[214:215], v156 offset:0x1400
	ds_read_b64_tr_b16 v[216:217], v156 offset:0x1c00
	v_mfma_f32_32x32x16_bf16 v[50:65], v[176:179], v[218:221], v[50:65]
	ds_read_b64_tr_b16 v[218:219], v156 offset:0x2400
	ds_read_b64_tr_b16 v[220:221], v156 offset:0x2c00
	v_mfma_f32_32x32x16_bf16 v[50:65], v[206:209], v[222:225], v[50:65]
	ds_read_b64_tr_b16 v[222:223], v156 offset:0x3400
	ds_read_b64_tr_b16 v[224:225], v156 offset:0x3c00
	s_waitcnt lgkmcnt(0)
	v_mfma_f32_32x32x16_bf16 v[34:49], v[182:185], v[210:213], v[34:49]
	ds_read_b64_tr_b16 v[210:211], v156 offset:0x600
	ds_read_b64_tr_b16 v[212:213], v156 offset:0xe00
	v_mfma_f32_32x32x16_bf16 v[34:49], v[202:205], v[214:217], v[34:49]
	ds_read_b64_tr_b16 v[214:215], v156 offset:0x1600
	ds_read_b64_tr_b16 v[216:217], v156 offset:0x1e00
	v_mfma_f32_32x32x16_bf16 v[34:49], v[176:179], v[218:221], v[34:49]
	ds_read_b64_tr_b16 v[218:219], v156 offset:0x2600
	ds_read_b64_tr_b16 v[220:221], v156 offset:0x2e00
	v_mfma_f32_32x32x16_bf16 v[34:49], v[206:209], v[222:225], v[34:49]
	ds_read_b64_tr_b16 v[222:223], v156 offset:0x3600
	ds_read_b64_tr_b16 v[224:225], v156 offset:0x3e00
	s_waitcnt lgkmcnt(0)
	v_mfma_f32_32x32x16_bf16 v[18:33], v[182:185], v[210:213], v[18:33]
	v_max_f32_e32 v156, v83, v83
	v_max_f32_e32 v157, v82, v82
	v_max_f32_e32 v156, v157, v156
	v_max3_f32 v156, v156, v84, v85
	v_max3_f32 v156, v156, v86, v87
	v_max3_f32 v156, v156, v88, v89
	v_max3_f32 v156, v156, v90, v91
	v_max3_f32 v156, v156, v92, v93
	v_max3_f32 v156, v156, v94, v95
	v_mfma_f32_32x32x16_bf16 v[18:33], v[202:205], v[214:217], v[18:33]
	v_max3_f32 v156, v156, v96, v97
	v_max3_f32 v156, v156, v66, v67
	v_max3_f32 v156, v156, v68, v69
	v_max3_f32 v156, v156, v70, v71
	v_max3_f32 v156, v156, v72, v73
	v_max3_f32 v156, v156, v74, v75
	v_max3_f32 v156, v156, v76, v77
	v_max3_f32 v156, v156, v78, v79
	v_mfma_f32_32x32x16_bf16 v[18:33], v[176:179], v[218:221], v[18:33]
	v_max3_f32 v156, v156, v80, v81
	v_mov_b32_e32 v157, v156
	s_nop 1
	v_permlane32_swap_b32_e32 v156, v157
	v_max_f32_e32 v157, v157, v157
	v_max_f32_e32 v156, v156, v156
	v_max_f32_e32 v156, v156, v157
	v_sub_f32_e32 v157, v156, v0
	v_cmp_ge_f32_e32 vcc, s27, v157
	v_max_f32_e32 v157, v0, v0
	v_max_f32_e32 v170, v157, v156
	v_mfma_f32_32x32x16_bf16 v[18:33], v[206:209], v[222:225], v[18:33]
	v_sub_f32_e32 v156, v0, v170
	v_mul_f32_e32 v156, 0x3dd53b94, v156
	v_exp_f32_e32 v156, v156
	s_cmp_eq_u64 vcc, exec
	s_cselect_b64 s[0:1], -1, 0
	v_cndmask_b32_e64 v168, v156, 1.0, s[0:1]
	v_cmp_gt_f32_e32 vcc, 1.0, v168
	s_cbranch_vccz .LBB2_343
	s_and_saveexec_b64 s[2:3], s[36:37]
	ds_write_b32 v194, v168 offset:128
	s_or_b64 exec, exec, s[2:3]
	s_waitcnt lgkmcnt(0)
	v_add_u32_e32 v156, s60, v162
	ds_read_b128 v[176:179], v156 offset:224
	ds_read_b128 v[182:185], v156 offset:192
	ds_read_b128 v[202:205], v156 offset:160
	ds_read_b128 v[206:209], v156 offset:128
	s_waitcnt lgkmcnt(0)
	v_pk_mul_f32 v[14:15], v[14:15], v[176:177]
	v_pk_mul_f32 v[10:11], v[10:11], v[182:183]
	v_pk_mul_f32 v[6:7], v[6:7], v[202:203]
	v_pk_mul_f32 v[16:17], v[16:17], v[178:179]
	v_pk_mul_f32 v[12:13], v[12:13], v[184:185]
	v_pk_mul_f32 v[8:9], v[8:9], v[204:205]
	v_pk_mul_f32 v[4:5], v[4:5], v[208:209]
	v_pk_mul_f32 v[2:3], v[2:3], v[206:207]
	v_pk_mul_f32 v[62:63], v[62:63], v[176:177]
	v_pk_mul_f32 v[58:59], v[58:59], v[182:183]
	v_pk_mul_f32 v[54:55], v[54:55], v[202:203]
	v_pk_mul_f32 v[64:65], v[64:65], v[178:179]
	v_pk_mul_f32 v[60:61], v[60:61], v[184:185]
	v_pk_mul_f32 v[56:57], v[56:57], v[204:205]
	v_pk_mul_f32 v[52:53], v[52:53], v[208:209]
	v_pk_mul_f32 v[50:51], v[50:51], v[206:207]
	v_pk_mul_f32 v[46:47], v[46:47], v[176:177]
	v_pk_mul_f32 v[42:43], v[42:43], v[182:183]
	v_pk_mul_f32 v[38:39], v[38:39], v[202:203]
	v_pk_mul_f32 v[48:49], v[48:49], v[178:179]
	v_pk_mul_f32 v[44:45], v[44:45], v[184:185]
	v_pk_mul_f32 v[40:41], v[40:41], v[204:205]
	v_pk_mul_f32 v[36:37], v[36:37], v[208:209]
	v_pk_mul_f32 v[34:35], v[34:35], v[206:207]
	v_pk_mul_f32 v[30:31], v[30:31], v[176:177]
	v_pk_mul_f32 v[26:27], v[26:27], v[182:183]
	v_pk_mul_f32 v[22:23], v[22:23], v[202:203]
	v_pk_mul_f32 v[32:33], v[32:33], v[178:179]
	v_pk_mul_f32 v[28:29], v[28:29], v[184:185]
	v_pk_mul_f32 v[24:25], v[24:25], v[204:205]
	v_pk_mul_f32 v[20:21], v[20:21], v[208:209]
	v_pk_mul_f32 v[18:19], v[18:19], v[206:207]
.LBB2_343:
	v_cndmask_b32_e64 v202, v170, v0, s[0:1]
	v_mul_f32_e32 v0, 0xbdd53b94, v202
	v_fmamk_f32 v82, v82, 0x3dd53b94, v0
	v_fmamk_f32 v83, v83, 0x3dd53b94, v0
	v_fmamk_f32 v84, v84, 0x3dd53b94, v0
	v_fmamk_f32 v85, v85, 0x3dd53b94, v0
	v_fmamk_f32 v86, v86, 0x3dd53b94, v0
	v_fmamk_f32 v87, v87, 0x3dd53b94, v0
	v_fmamk_f32 v88, v88, 0x3dd53b94, v0
	v_fmamk_f32 v89, v89, 0x3dd53b94, v0
	v_fmamk_f32 v90, v90, 0x3dd53b94, v0
	v_fmamk_f32 v91, v91, 0x3dd53b94, v0
	v_fmamk_f32 v92, v92, 0x3dd53b94, v0
	v_fmamk_f32 v93, v93, 0x3dd53b94, v0
	v_fmamk_f32 v94, v94, 0x3dd53b94, v0
	v_fmamk_f32 v95, v95, 0x3dd53b94, v0
	v_fmamk_f32 v96, v96, 0x3dd53b94, v0
	v_fmamk_f32 v97, v97, 0x3dd53b94, v0
	v_exp_f32_e32 v216, v82
	v_exp_f32_e32 v218, v83
	v_exp_f32_e32 v214, v84
	v_exp_f32_e32 v217, v85
	v_exp_f32_e32 v212, v86
	v_exp_f32_e32 v215, v87
	v_exp_f32_e32 v211, v88
	v_exp_f32_e32 v213, v89
	v_exp_f32_e32 v208, v90
	v_exp_f32_e32 v210, v91
	v_exp_f32_e32 v206, v92
	v_exp_f32_e32 v209, v93
	v_exp_f32_e32 v204, v94
	v_exp_f32_e32 v207, v95
	v_exp_f32_e32 v203, v96
	v_exp_f32_e32 v205, v97
	s_mov_b64 s[0:1], -1
	s_and_b64 vcc, exec, s[18:19]
	s_cbranch_vccz .LBB2_345
	s_waitcnt vmcnt(0) lgkmcnt(0)
	s_mov_b64 s[0:1], 0
.LBB2_345:
	s_andn2_b64 vcc, exec, s[0:1]
	s_cbranch_vccnz .LBB2_347
	s_waitcnt vmcnt(5) lgkmcnt(0)
.LBB2_347:
	s_add_i32 s11, s11, 2
	s_xor_b32 s64, s64, 2
	s_xor_b32 s63, s63, 2
	s_add_i32 s0, s25, 1
	s_cmp_lg_u32 s25, 2
	s_cselect_b32 s40, s0, 0
	s_add_i32 s0, s24, 1
	s_cmp_lg_u32 s24, 2
	v_add_f32_e32 v82, v172, v173
	s_barrier
	s_cselect_b32 s24, s0, 0
	s_mov_b64 s[0:1], 0x60000
	v_fmac_f32_e32 v82, v201, v195
	v_add_f32_e32 v195, v169, v180
	v_lshl_add_u64 v[164:165], v[164:165], 0, s[0:1]
	s_mov_b64 s[0:1], 0x40000
	v_fmac_f32_e32 v195, v82, v174
	v_pk_fma_f32 v[186:187], v[66:67], s[26:27], v[0:1] op_sel_hi:[1,0,0]
	v_pk_fma_f32 v[184:185], v[68:69], s[26:27], v[0:1] op_sel_hi:[1,0,0]
	v_pk_fma_f32 v[182:183], v[70:71], s[26:27], v[0:1] op_sel_hi:[1,0,0]
	v_pk_fma_f32 v[180:181], v[72:73], s[26:27], v[0:1] op_sel_hi:[1,0,0]
	v_pk_fma_f32 v[178:179], v[74:75], s[26:27], v[0:1] op_sel_hi:[1,0,0]
	v_pk_fma_f32 v[176:177], v[76:77], s[26:27], v[0:1] op_sel_hi:[1,0,0]
	v_pk_fma_f32 v[174:175], v[78:79], s[26:27], v[0:1] op_sel_hi:[1,0,0]
	v_pk_fma_f32 v[172:173], v[80:81], s[26:27], v[0:1] op_sel_hi:[1,0,0]
	v_lshl_add_u64 v[166:167], v[166:167], 0, s[0:1]
	s_and_b64 vcc, exec, s[18:19]
	s_cbranch_vccnz .LBB2_349
	v_mov_b32_e32 v201, v168
	s_branch .LBB2_333
.LBB2_349:
	s_add_i32 s0, 0, 0x12000
	v_add_u32_e32 v0, s0, v197
	v_add_u32_e32 v156, s0, v198
	v_add_u32_e32 v157, s0, v199
	v_add_u32_e32 v158, s0, v200
	ds_read_b128 v[66:69], v0 offset:0
	ds_read_b128 v[70:73], v0 offset:0x1000
	ds_read_b128 v[164:167], v156 offset:0
	ds_read_b128 v[198:201], v156 offset:0x1000
	ds_read_b128 v[220:223], v157 offset:0
	ds_read_b128 v[224:227], v157 offset:0x1000
	s_setprio 1
	s_waitcnt lgkmcnt(4)
	s_nop 0
	v_mfma_f32_32x32x16_bf16 v[82:97], v[66:69], v[142:145], 0
	v_mfma_f32_32x32x16_bf16 v[66:81], v[70:73], v[142:145], 0
	ds_read_b128 v[142:145], v158 offset:0
	ds_read_b128 v[228:231], v158 offset:0x1000
	s_waitcnt lgkmcnt(4)
	s_nop 0
	v_mfma_f32_32x32x16_bf16 v[82:97], v[164:167], v[138:141], v[82:97]
	v_mfma_f32_32x32x16_bf16 v[66:81], v[198:201], v[138:141], v[66:81]
	ds_read_b128 v[138:141], v0 offset:0x2000
	ds_read_b128 v[164:167], v0 offset:0x3000
	s_waitcnt lgkmcnt(4)
	s_nop 0
	v_mfma_f32_32x32x16_bf16 v[82:97], v[220:223], v[134:137], v[82:97]
	v_mfma_f32_32x32x16_bf16 v[66:81], v[224:227], v[134:137], v[66:81]
	ds_read_b128 v[134:137], v156 offset:0x2000
	ds_read_b128 v[198:201], v156 offset:0x3000
	s_waitcnt lgkmcnt(4)
	s_nop 0
	v_mfma_f32_32x32x16_bf16 v[82:97], v[142:145], v[130:133], v[82:97]
	v_mfma_f32_32x32x16_bf16 v[66:81], v[228:231], v[130:133], v[66:81]
	ds_read_b128 v[130:133], v157 offset:0x2000
	ds_read_b128 v[142:145], v157 offset:0x3000
	s_waitcnt lgkmcnt(4)
	s_nop 0
	v_mfma_f32_32x32x16_bf16 v[82:97], v[138:141], v[126:129], v[82:97]
	v_mfma_f32_32x32x16_bf16 v[66:81], v[164:167], v[126:129], v[66:81]
	ds_read_b128 v[126:129], v158 offset:0x2000
	ds_read_b128 v[138:141], v158 offset:0x3000
	s_waitcnt lgkmcnt(4)
	s_nop 0
	v_mfma_f32_32x32x16_bf16 v[82:97], v[134:137], v[122:125], v[82:97]
	v_mfma_f32_32x32x16_bf16 v[66:81], v[198:201], v[122:125], v[66:81]
	ds_read_b128 v[122:125], v0 offset:0x4000
	ds_read_b128 v[134:137], v0 offset:0x5000
	s_waitcnt lgkmcnt(4)
	s_nop 0
	v_mfma_f32_32x32x16_bf16 v[82:97], v[130:133], v[118:121], v[82:97]
	v_mfma_f32_32x32x16_bf16 v[66:81], v[142:145], v[118:121], v[66:81]
	ds_read_b128 v[118:121], v156 offset:0x4000
	ds_read_b128 v[130:133], v156 offset:0x5000
	s_waitcnt lgkmcnt(4)
	s_nop 0
	v_mfma_f32_32x32x16_bf16 v[82:97], v[126:129], v[114:117], v[82:97]
	v_mfma_f32_32x32x16_bf16 v[66:81], v[138:141], v[114:117], v[66:81]
	ds_read_b128 v[114:117], v157 offset:0x4000
	ds_read_b128 v[126:129], v157 offset:0x5000
	s_waitcnt lgkmcnt(4)
	s_nop 0
	v_mfma_f32_32x32x16_bf16 v[82:97], v[122:125], v[110:113], v[82:97]
	v_mfma_f32_32x32x16_bf16 v[66:81], v[134:137], v[110:113], v[66:81]
	ds_read_b128 v[110:113], v158 offset:0x4000
	ds_read_b128 v[122:125], v158 offset:0x5000
	s_waitcnt lgkmcnt(4)
	s_waitcnt lgkmcnt(2)
	s_nop 0
	s_waitcnt lgkmcnt(0)
	v_mfma_f32_32x32x16_bf16 v[82:97], v[118:121], v[106:109], v[82:97]
	v_mfma_f32_32x32x16_bf16 v[66:81], v[130:133], v[106:109], v[66:81]
	v_mfma_f32_32x32x16_bf16 v[82:97], v[114:117], v[102:105], v[82:97]
	v_mfma_f32_32x32x16_bf16 v[66:81], v[126:129], v[102:105], v[66:81]
	v_mfma_f32_32x32x16_bf16 v[82:97], v[110:113], v[98:101], v[82:97]
	v_mfma_f32_32x32x16_bf16 v[66:81], v[122:125], v[98:101], v[66:81]
	s_setprio 0
	v_add_f32_e32 v0, 0, v216
	v_add_f32_e32 v0, v218, v0
	v_add_f32_e32 v0, v214, v0
	v_add_f32_e32 v0, v217, v0
	v_add_f32_e32 v0, v212, v0
	v_add_f32_e32 v0, v215, v0
	v_add_f32_e32 v0, v211, v0
	v_add_f32_e32 v0, v213, v0
	v_add_f32_e32 v0, v208, v0
	v_add_f32_e32 v0, v210, v0
	v_add_f32_e32 v0, v206, v0
	v_add_f32_e32 v0, v209, v0
	v_exp_f32_e32 v99, v186
	v_add_f32_e32 v0, v204, v0
	v_exp_f32_e32 v108, v187
	v_add_f32_e32 v0, v207, v0
	v_exp_f32_e32 v109, v184
	v_add_f32_e32 v0, v203, v0
	v_exp_f32_e32 v110, v185
	v_add_f32_e32 v0, v205, v0
	v_exp_f32_e32 v111, v182
	v_add_f32_e32 v0, v99, v0
	v_exp_f32_e32 v112, v183
	v_add_f32_e32 v0, v108, v0
	v_exp_f32_e32 v113, v180
	v_add_f32_e32 v0, v109, v0
	v_exp_f32_e32 v114, v181
	v_add_f32_e32 v0, v110, v0
	v_exp_f32_e32 v115, v178
	v_add_f32_e32 v0, v111, v0
	v_exp_f32_e32 v116, v179
	v_add_f32_e32 v0, v112, v0
	v_exp_f32_e32 v117, v176
	v_add_f32_e32 v0, v113, v0
	v_exp_f32_e32 v118, v177
	v_add_f32_e32 v0, v114, v0
	v_exp_f32_e32 v119, v174
	v_add_f32_e32 v0, v115, v0
	v_exp_f32_e32 v120, v175
	v_add_f32_e32 v0, v116, v0
	v_exp_f32_e32 v121, v172
	v_add_f32_e32 v0, v117, v0
	v_exp_f32_e32 v122, v173
	v_add_f32_e32 v0, v118, v0
	v_add_f32_e32 v0, v119, v0
	v_add_f32_e32 v0, v120, v0
	v_add_f32_e32 v0, v121, v0
	v_add_f32_e32 v0, v122, v0
	v_mov_b32_e32 v98, v0
	v_cvt_pk_bf16_f32 v100, v216, v218
	v_cvt_pk_bf16_f32 v101, v214, v217
	v_cvt_pk_bf16_f32 v102, v212, v215
	s_nop 1
	v_permlane32_swap_b32_e32 v0, v98
	v_cvt_pk_bf16_f32 v103, v211, v213
	v_permlane32_swap_b32_e32 v100, v102
	v_cvt_pk_bf16_f32 v104, v208, v210
	v_cvt_pk_bf16_f32 v105, v206, v209
	v_cvt_pk_bf16_f32 v106, v204, v207
	v_cvt_pk_bf16_f32 v107, v203, v205
	v_cvt_pk_bf16_f32 v108, v99, v108
	v_cvt_pk_bf16_f32 v109, v109, v110
	v_cvt_pk_bf16_f32 v110, v111, v112
	v_cvt_pk_bf16_f32 v111, v113, v114
	v_cvt_pk_bf16_f32 v112, v115, v116
	v_cvt_pk_bf16_f32 v113, v117, v118
	v_cvt_pk_bf16_f32 v114, v119, v120
	v_cvt_pk_bf16_f32 v115, v121, v122
	v_permlane32_swap_b32_e32 v101, v103
	v_permlane32_swap_b32_e32 v104, v106
	v_permlane32_swap_b32_e32 v105, v107
	v_permlane32_swap_b32_e32 v108, v110
	v_permlane32_swap_b32_e32 v109, v111
	v_permlane32_swap_b32_e32 v112, v114
	v_permlane32_swap_b32_e32 v113, v115
	ds_read_b64_tr_b16 v[116:117], v196 offset:0
	ds_read_b64_tr_b16 v[118:119], v196 offset:0x800
	ds_read_b64_tr_b16 v[120:121], v196 offset:0x1000
	ds_read_b64_tr_b16 v[122:123], v196 offset:0x1800
	ds_read_b64_tr_b16 v[124:125], v196 offset:0x2000
	ds_read_b64_tr_b16 v[126:127], v196 offset:0x2800
	ds_read_b64_tr_b16 v[128:129], v196 offset:0x3000
	ds_read_b64_tr_b16 v[130:131], v196 offset:0x3800
	s_waitcnt lgkmcnt(0)
	s_nop 0
	v_mfma_f32_32x32x16_bf16 v[2:17], v[100:103], v[116:119], v[2:17]
	ds_read_b64_tr_b16 v[116:117], v196 offset:0x200
	ds_read_b64_tr_b16 v[118:119], v196 offset:0xa00
	v_mfma_f32_32x32x16_bf16 v[2:17], v[104:107], v[120:123], v[2:17]
	ds_read_b64_tr_b16 v[120:121], v196 offset:0x1200
	ds_read_b64_tr_b16 v[122:123], v196 offset:0x1a00
	v_mfma_f32_32x32x16_bf16 v[2:17], v[108:111], v[124:127], v[2:17]
	ds_read_b64_tr_b16 v[124:125], v196 offset:0x2200
	ds_read_b64_tr_b16 v[126:127], v196 offset:0x2a00
	v_mfma_f32_32x32x16_bf16 v[2:17], v[112:115], v[128:131], v[2:17]
	ds_read_b64_tr_b16 v[128:129], v196 offset:0x3200
	ds_read_b64_tr_b16 v[130:131], v196 offset:0x3a00
	s_waitcnt lgkmcnt(0)
	v_mfma_f32_32x32x16_bf16 v[50:65], v[100:103], v[116:119], v[50:65]
	ds_read_b64_tr_b16 v[116:117], v196 offset:0x400
	ds_read_b64_tr_b16 v[118:119], v196 offset:0xc00
	v_mfma_f32_32x32x16_bf16 v[50:65], v[104:107], v[120:123], v[50:65]
	ds_read_b64_tr_b16 v[120:121], v196 offset:0x1400
	ds_read_b64_tr_b16 v[122:123], v196 offset:0x1c00
	v_mfma_f32_32x32x16_bf16 v[50:65], v[108:111], v[124:127], v[50:65]
	ds_read_b64_tr_b16 v[124:125], v196 offset:0x2400
	ds_read_b64_tr_b16 v[126:127], v196 offset:0x2c00
	v_mfma_f32_32x32x16_bf16 v[50:65], v[112:115], v[128:131], v[50:65]
	ds_read_b64_tr_b16 v[128:129], v196 offset:0x3400
	ds_read_b64_tr_b16 v[130:131], v196 offset:0x3c00
	s_waitcnt lgkmcnt(0)
	v_mfma_f32_32x32x16_bf16 v[34:49], v[100:103], v[116:119], v[34:49]
	ds_read_b64_tr_b16 v[116:117], v196 offset:0x600
	ds_read_b64_tr_b16 v[118:119], v196 offset:0xe00
	v_mfma_f32_32x32x16_bf16 v[34:49], v[104:107], v[120:123], v[34:49]
	ds_read_b64_tr_b16 v[120:121], v196 offset:0x1600
	ds_read_b64_tr_b16 v[122:123], v196 offset:0x1e00
	v_mfma_f32_32x32x16_bf16 v[34:49], v[108:111], v[124:127], v[34:49]
	ds_read_b64_tr_b16 v[124:125], v196 offset:0x2600
	ds_read_b64_tr_b16 v[126:127], v196 offset:0x2e00
	v_mfma_f32_32x32x16_bf16 v[34:49], v[112:115], v[128:131], v[34:49]
	ds_read_b64_tr_b16 v[128:129], v196 offset:0x3600
	ds_read_b64_tr_b16 v[130:131], v196 offset:0x3e00
	s_waitcnt lgkmcnt(0)
	v_mfma_f32_32x32x16_bf16 v[18:33], v[100:103], v[116:119], v[18:33]
	v_max_f32_e32 v99, v83, v83
	v_max_f32_e32 v100, v82, v82
	v_max_f32_e32 v99, v100, v99
	v_max3_f32 v99, v99, v84, v85
	v_max3_f32 v99, v99, v86, v87
	v_max3_f32 v99, v99, v88, v89
	v_max3_f32 v99, v99, v90, v91
	v_max3_f32 v99, v99, v92, v93
	v_max3_f32 v99, v99, v94, v95
	v_mfma_f32_32x32x16_bf16 v[18:33], v[104:107], v[120:123], v[18:33]
	v_max3_f32 v99, v99, v96, v97
	v_max3_f32 v99, v99, v66, v67
	v_max3_f32 v99, v99, v68, v69
	v_max3_f32 v99, v99, v70, v71
	v_max3_f32 v99, v99, v72, v73
	v_max3_f32 v99, v99, v74, v75
	v_max3_f32 v99, v99, v76, v77
	v_max3_f32 v99, v99, v78, v79
	v_mfma_f32_32x32x16_bf16 v[18:33], v[108:111], v[124:127], v[18:33]
	v_max3_f32 v99, v99, v80, v81
	v_mov_b32_e32 v100, v99
	s_nop 1
	v_permlane32_swap_b32_e32 v99, v100
	v_max_f32_e32 v100, v100, v100
	v_max_f32_e32 v99, v99, v99
	v_max_f32_e32 v99, v99, v100
	v_sub_f32_e32 v100, v99, v202
	v_cmp_ge_f32_e32 vcc, s27, v100
	v_max_f32_e32 v100, v202, v202
	v_max_f32_e32 v100, v100, v99
	v_mfma_f32_32x32x16_bf16 v[18:33], v[112:115], v[128:131], v[18:33]
	v_sub_f32_e32 v99, v202, v100
	v_mul_f32_e32 v99, 0x3dd53b94, v99
	v_exp_f32_e32 v99, v99
	s_cmp_eq_u64 vcc, exec
	s_cselect_b64 s[0:1], -1, 0
	v_cndmask_b32_e64 v99, v99, 1.0, s[0:1]
	v_cmp_gt_f32_e32 vcc, 1.0, v99
	s_cbranch_vccz .LBB2_353
	s_and_saveexec_b64 s[2:3], s[36:37]
	ds_write_b32 v194, v99 offset:128
	s_or_b64 exec, exec, s[2:3]
	s_waitcnt lgkmcnt(0)
	v_add_u32_e32 v101, s60, v162
	ds_read_b128 v[102:105], v101 offset:224
	ds_read_b128 v[106:109], v101 offset:192
	ds_read_b128 v[110:113], v101 offset:160
	ds_read_b128 v[114:117], v101 offset:128
	s_waitcnt lgkmcnt(0)
	v_pk_mul_f32 v[14:15], v[14:15], v[102:103]
	v_pk_mul_f32 v[10:11], v[10:11], v[106:107]
	v_pk_mul_f32 v[6:7], v[6:7], v[110:111]
	v_pk_mul_f32 v[16:17], v[16:17], v[104:105]
	v_pk_mul_f32 v[12:13], v[12:13], v[108:109]
	v_pk_mul_f32 v[8:9], v[8:9], v[112:113]
	v_pk_mul_f32 v[4:5], v[4:5], v[116:117]
	v_pk_mul_f32 v[2:3], v[2:3], v[114:115]
	v_pk_mul_f32 v[62:63], v[62:63], v[102:103]
	v_pk_mul_f32 v[58:59], v[58:59], v[106:107]
	v_pk_mul_f32 v[54:55], v[54:55], v[110:111]
	v_pk_mul_f32 v[64:65], v[64:65], v[104:105]
	v_pk_mul_f32 v[60:61], v[60:61], v[108:109]
	v_pk_mul_f32 v[56:57], v[56:57], v[112:113]
	v_pk_mul_f32 v[52:53], v[52:53], v[116:117]
	v_pk_mul_f32 v[50:51], v[50:51], v[114:115]
	v_pk_mul_f32 v[46:47], v[46:47], v[102:103]
	v_pk_mul_f32 v[42:43], v[42:43], v[106:107]
	v_pk_mul_f32 v[38:39], v[38:39], v[110:111]
	v_pk_mul_f32 v[48:49], v[48:49], v[104:105]
	v_pk_mul_f32 v[44:45], v[44:45], v[108:109]
	v_pk_mul_f32 v[40:41], v[40:41], v[112:113]
	v_pk_mul_f32 v[36:37], v[36:37], v[116:117]
	v_pk_mul_f32 v[34:35], v[34:35], v[114:115]
	v_pk_mul_f32 v[30:31], v[30:31], v[102:103]
	v_pk_mul_f32 v[26:27], v[26:27], v[106:107]
	v_pk_mul_f32 v[22:23], v[22:23], v[110:111]
	v_pk_mul_f32 v[32:33], v[32:33], v[104:105]
	v_pk_mul_f32 v[28:29], v[28:29], v[108:109]
	v_pk_mul_f32 v[24:25], v[24:25], v[112:113]
	v_pk_mul_f32 v[20:21], v[20:21], v[116:117]
	v_pk_mul_f32 v[18:19], v[18:19], v[114:115]

.LBB2_708:
	v_readlane_b32 s52, v252, 23
	v_lshl_add_u32 v142, s15, 8, v160
	v_readlane_b32 s64, v252, 35
	v_readlane_b32 s65, v252, 36
	v_lshl_or_b32 v140, s14, 8, v162
	v_ashrrev_i32_e32 v143, 31, v142
	v_readlane_b32 s66, v252, 37
	v_readlane_b32 s67, v252, 38
	s_mov_b64 s[20:21], s[64:65]
	v_ashrrev_i32_e32 v141, 31, v140
	v_lshlrev_b64 v[144:145], 13, v[142:143]
	s_mov_b64 s[22:23], s[66:67]
	v_lshl_add_u64 v[156:157], s[22:23], 0, v[144:145]
	v_lshlrev_b64 v[144:145], 2, v[140:141]
	v_lshl_add_u64 v[140:141], v[156:157], 0, v[144:145]
	v_readlane_b32 s53, v252, 24
	v_readlane_b32 s54, v252, 25
	v_readlane_b32 s55, v252, 26
	v_readlane_b32 s56, v252, 27
	v_readlane_b32 s57, v252, 28
	v_readlane_b32 s58, v252, 29
	v_readlane_b32 s59, v252, 30
	v_readlane_b32 s60, v252, 31
	v_readlane_b32 s61, v252, 32
	v_readlane_b32 s62, v252, 33
	v_readlane_b32 s63, v252, 34
	v_mov_b32_e32 v142, v140
	v_mov_b32_e32 v143, v141
	s_mov_b64 s[100:101], 0x20000
	global_load_dwordx4 v[192:195], v[140:141], off
	global_load_dwordx4 v[196:199], v[140:141], off offset:16
	global_load_dwordx4 v[200:203], v[140:141], off offset:512
	global_load_dwordx4 v[204:207], v[140:141], off offset:528
	v_lshl_add_u64 v[140:141], v[140:141], 0, s[100:101]
	global_load_dwordx4 v[208:211], v[140:141], off
	global_load_dwordx4 v[212:215], v[140:141], off offset:16
	global_load_dwordx4 v[216:219], v[140:141], off offset:512
	global_load_dwordx4 v[220:223], v[140:141], off offset:528
	v_lshl_add_u64 v[140:141], v[140:141], 0, s[100:101]
	global_load_dwordx4 v[224:227], v[140:141], off
	global_load_dwordx4 v[228:231], v[140:141], off offset:16
	global_load_dwordx4 v[232:235], v[140:141], off offset:512
	global_load_dwordx4 v[236:239], v[140:141], off offset:528
	v_lshl_add_u64 v[140:141], v[140:141], 0, s[100:101]
	global_load_dwordx4 v[170:173], v[140:141], off
	global_load_dwordx4 v[174:177], v[140:141], off offset:16
	global_load_dwordx4 v[178:181], v[140:141], off offset:512
	global_load_dwordx4 v[182:185], v[140:141], off offset:528
	v_lshl_add_u64 v[140:141], s[100:101], 2, v[140:141]
	v_lshl_add_u64 v[140:141], v[140:141], 0, s[100:101]
	s_waitcnt vmcnt(12)
	v_pk_add_f32 v[126:127], v[126:127], v[192:193]
	v_pk_add_f32 v[128:129], v[128:129], v[194:195]
	v_pk_add_f32 v[122:123], v[122:123], v[196:197]
	v_pk_add_f32 v[124:125], v[124:125], v[198:199]
	v_pk_add_f32 v[118:119], v[118:119], v[200:201]
	v_pk_add_f32 v[120:121], v[120:121], v[202:203]
	v_pk_add_f32 v[114:115], v[114:115], v[204:205]
	v_pk_add_f32 v[116:117], v[116:117], v[206:207]
	global_store_dwordx4 v[142:143], v[126:129], off
	global_store_dwordx4 v[142:143], v[122:125], off offset:16
	global_store_dwordx4 v[142:143], v[118:121], off offset:512
	global_store_dwordx4 v[142:143], v[114:117], off offset:528
	v_lshl_add_u64 v[142:143], v[142:143], 0, s[100:101]
	global_load_dwordx4 v[192:195], v[140:141], off
	global_load_dwordx4 v[196:199], v[140:141], off offset:16
	global_load_dwordx4 v[200:203], v[140:141], off offset:512
	global_load_dwordx4 v[204:207], v[140:141], off offset:528
	v_lshl_add_u64 v[140:141], v[140:141], 0, s[100:101]
	s_waitcnt vmcnt(16)
	v_pk_add_f32 v[110:111], v[110:111], v[208:209]
	v_pk_add_f32 v[112:113], v[112:113], v[210:211]
	v_pk_add_f32 v[106:107], v[106:107], v[212:213]
	v_pk_add_f32 v[108:109], v[108:109], v[214:215]
	v_pk_add_f32 v[102:103], v[102:103], v[216:217]
	v_pk_add_f32 v[104:105], v[104:105], v[218:219]
	v_pk_add_f32 v[98:99], v[98:99], v[220:221]
	v_pk_add_f32 v[100:101], v[100:101], v[222:223]
	global_store_dwordx4 v[142:143], v[110:113], off
	global_store_dwordx4 v[142:143], v[106:109], off offset:16
	global_store_dwordx4 v[142:143], v[102:105], off offset:512
	global_store_dwordx4 v[142:143], v[98:101], off offset:528
	v_lshl_add_u64 v[142:143], v[142:143], 0, s[100:101]
	global_load_dwordx4 v[208:211], v[140:141], off
	global_load_dwordx4 v[212:215], v[140:141], off offset:16
	global_load_dwordx4 v[216:219], v[140:141], off offset:512
	global_load_dwordx4 v[220:223], v[140:141], off offset:528
	v_lshl_add_u64 v[140:141], v[140:141], 0, s[100:101]
	s_waitcnt vmcnt(20)
	v_pk_add_f32 v[94:95], v[94:95], v[224:225]
	v_pk_add_f32 v[96:97], v[96:97], v[226:227]
	v_pk_add_f32 v[90:91], v[90:91], v[228:229]
	v_pk_add_f32 v[92:93], v[92:93], v[230:231]
	v_pk_add_f32 v[86:87], v[86:87], v[232:233]
	v_pk_add_f32 v[88:89], v[88:89], v[234:235]
	v_pk_add_f32 v[82:83], v[82:83], v[236:237]
	v_pk_add_f32 v[84:85], v[84:85], v[238:239]
	global_store_dwordx4 v[142:143], v[94:97], off
	global_store_dwordx4 v[142:143], v[90:93], off offset:16
	global_store_dwordx4 v[142:143], v[86:89], off offset:512
	global_store_dwordx4 v[142:143], v[82:85], off offset:528
	v_lshl_add_u64 v[142:143], v[142:143], 0, s[100:101]
	global_load_dwordx4 v[224:227], v[140:141], off
	global_load_dwordx4 v[228:231], v[140:141], off offset:16
	global_load_dwordx4 v[232:235], v[140:141], off offset:512
	global_load_dwordx4 v[236:239], v[140:141], off offset:528
	v_lshl_add_u64 v[140:141], v[140:141], 0, s[100:101]
	s_waitcnt vmcnt(24)
	v_pk_add_f32 v[78:79], v[78:79], v[170:171]
	v_pk_add_f32 v[80:81], v[80:81], v[172:173]
	v_pk_add_f32 v[74:75], v[74:75], v[174:175]
	v_pk_add_f32 v[76:77], v[76:77], v[176:177]
	v_pk_add_f32 v[70:71], v[70:71], v[178:179]
	v_pk_add_f32 v[72:73], v[72:73], v[180:181]
	v_pk_add_f32 v[66:67], v[66:67], v[182:183]
	v_pk_add_f32 v[68:69], v[68:69], v[184:185]
	global_store_dwordx4 v[142:143], v[78:81], off
	global_store_dwordx4 v[142:143], v[74:77], off offset:16
	global_store_dwordx4 v[142:143], v[70:73], off offset:512
	global_store_dwordx4 v[142:143], v[66:69], off offset:528
	v_lshl_add_u64 v[142:143], s[100:101], 2, v[142:143]
	v_lshl_add_u64 v[142:143], v[142:143], 0, s[100:101]
	global_load_dwordx4 v[170:173], v[140:141], off
	global_load_dwordx4 v[174:177], v[140:141], off offset:16
	global_load_dwordx4 v[178:181], v[140:141], off offset:512
	global_load_dwordx4 v[182:185], v[140:141], off offset:528
	s_waitcnt vmcnt(24)
	v_pk_add_f32 v[62:63], v[62:63], v[192:193]
	v_pk_add_f32 v[64:65], v[64:65], v[194:195]
	v_pk_add_f32 v[58:59], v[58:59], v[196:197]
	v_pk_add_f32 v[60:61], v[60:61], v[198:199]
	v_pk_add_f32 v[54:55], v[54:55], v[200:201]
	v_pk_add_f32 v[56:57], v[56:57], v[202:203]
	v_pk_add_f32 v[50:51], v[50:51], v[204:205]
	v_pk_add_f32 v[52:53], v[52:53], v[206:207]
	global_store_dwordx4 v[142:143], v[62:65], off
	global_store_dwordx4 v[142:143], v[58:61], off offset:16
	global_store_dwordx4 v[142:143], v[54:57], off offset:512
	global_store_dwordx4 v[142:143], v[50:53], off offset:528
	v_lshl_add_u64 v[142:143], v[142:143], 0, s[100:101]
	s_waitcnt vmcnt(20)
	v_pk_add_f32 v[46:47], v[46:47], v[208:209]
	v_pk_add_f32 v[48:49], v[48:49], v[210:211]
	v_pk_add_f32 v[42:43], v[42:43], v[212:213]
	v_pk_add_f32 v[44:45], v[44:45], v[214:215]
	v_pk_add_f32 v[38:39], v[38:39], v[216:217]
	v_pk_add_f32 v[40:41], v[40:41], v[218:219]
	v_pk_add_f32 v[34:35], v[34:35], v[220:221]
	v_pk_add_f32 v[36:37], v[36:37], v[222:223]
	global_store_dwordx4 v[142:143], v[46:49], off
	global_store_dwordx4 v[142:143], v[42:45], off offset:16
	global_store_dwordx4 v[142:143], v[38:41], off offset:512
	global_store_dwordx4 v[142:143], v[34:37], off offset:528
	v_lshl_add_u64 v[142:143], v[142:143], 0, s[100:101]
	s_waitcnt vmcnt(16)
	v_pk_add_f32 v[30:31], v[30:31], v[224:225]
	v_pk_add_f32 v[32:33], v[32:33], v[226:227]
	v_pk_add_f32 v[26:27], v[26:27], v[228:229]
	v_pk_add_f32 v[28:29], v[28:29], v[230:231]
	v_pk_add_f32 v[22:23], v[22:23], v[232:233]
	v_pk_add_f32 v[24:25], v[24:25], v[234:235]
	v_pk_add_f32 v[18:19], v[18:19], v[236:237]
	v_pk_add_f32 v[20:21], v[20:21], v[238:239]
	global_store_dwordx4 v[142:143], v[30:33], off
	global_store_dwordx4 v[142:143], v[26:29], off offset:16
	global_store_dwordx4 v[142:143], v[22:25], off offset:512
	global_store_dwordx4 v[142:143], v[18:21], off offset:528
	v_lshl_add_u64 v[142:143], v[142:143], 0, s[100:101]
	s_waitcnt vmcnt(12)
	v_pk_add_f32 v[14:15], v[14:15], v[170:171]
	v_pk_add_f32 v[16:17], v[16:17], v[172:173]
	v_pk_add_f32 v[10:11], v[10:11], v[174:175]
	v_pk_add_f32 v[12:13], v[12:13], v[176:177]
	v_pk_add_f32 v[6:7], v[6:7], v[178:179]
	v_pk_add_f32 v[8:9], v[8:9], v[180:181]
	v_pk_add_f32 v[2:3], v[2:3], v[182:183]
	v_pk_add_f32 v[4:5], v[4:5], v[184:185]
	global_store_dwordx4 v[142:143], v[14:17], off
	global_store_dwordx4 v[142:143], v[10:13], off offset:16
	global_store_dwordx4 v[142:143], v[6:9], off offset:512
	global_store_dwordx4 v[142:143], v[2:5], off offset:528
	s_mov_b64 s[2:3], -1
	s_andn2_b64 vcc, exec, s[38:39]
	s_cbranch_vccnz .LBB2_697
	s_andn2_b64 vcc, exec, s[0:1]
	s_cbranch_vccnz .LBB2_696
	s_barrier
	s_branch .LBB2_696
